# mLSTM: output-gate (OM) row loads also spread through step 4 with vt loads; head-norm gain load hoisted out of chunk loop; raw loads in step 3
# speedup vs baseline: 1.0120x; 1.0028x over previous
.LBB0_135:
	v_mov_b32_e32 v0, v222
	s_add_i32 s2, 0, 0x18400
	v_lshlrev_b32_e32 v0, 3, v0
	v_and_b32_e32 v96, 0x1f8, v0
	v_add_u32_e32 v12, s2, v96
	v_add_u32_e32 v0, s16, v12
	ds_read_b64 v[0:1], v0
	s_waitcnt vmcnt(7)
	v_and_b32_e32 v11, 0xffff0000, v206
	v_lshlrev_b32_e32 v13, 16, v207
	v_mul_f32_e32 v11, 0xbfb8aa3b, v11
	v_mul_f32_e32 v13, 0xbfb8aa3b, v13
	s_waitcnt lgkmcnt(0)
	v_and_b32_e32 v3, 0xffff0000, v1
	v_and_b32_e32 v5, 0xffff0000, v0
	v_lshlrev_b32_e32 v2, 16, v1
	v_lshlrev_b32_e32 v4, 16, v0
	v_mov_b32_e32 v6, v5
	v_mov_b32_e32 v7, v3
	v_mov_b32_e32 v0, v4
	v_mov_b32_e32 v1, v2
	v_pk_mul_f32 v[6:7], v[6:7], v[6:7]
	v_exp_f32_e32 v11, v11
	v_pk_fma_f32 v[0:1], v[0:1], v[0:1], v[6:7]
	v_exp_f32_e32 v13, v13
	v_add_f32_e32 v6, v0, v1
	ds_bpermute_b32 v7, v189, v6
	v_lshlrev_b32_e32 v8, 16, v206
	v_mul_f32_e32 v8, 0xbfb8aa3b, v8
	v_exp_f32_e32 v8, v8
	s_or_b32 s2, s18, 0x7c0
	s_waitcnt lgkmcnt(0)
	v_add_f32_e32 v6, v6, v7
	ds_bpermute_b32 v7, v191, v6
	v_add_f32_e32 v8, 1.0, v8
	v_rcp_f32_e32 v8, v8
	s_add_u32 s12, s2, s63
	s_addc_u32 s13, s19, 0
	s_waitcnt lgkmcnt(0)
	v_add_f32_e32 v9, v6, v7
	ds_bpermute_b32 v10, v209, v9
	v_lshl_add_u64 v[0:1], s[46:47], 0, v[96:97]
	s_lshl_b64 s[12:13], s[12:13], 11
	v_lshl_add_u64 v[6:7], v[0:1], 0, s[12:13]
	s_add_u32 s12, s2, s92
	s_waitcnt lgkmcnt(0)
	v_add_f32_e32 v9, v9, v10
	ds_bpermute_b32 v10, v210, v9
	s_addc_u32 s13, s19, 0
	s_lshl_b64 s[12:13], s[12:13], 11
	v_readlane_b32 s56, v255, 4
	v_readlane_b32 s97, v254, 48
	s_waitcnt lgkmcnt(0)
	v_add_f32_e32 v10, v9, v10
	ds_bpermute_b32 v14, v211, v10
	v_add_f32_e32 v9, 1.0, v11
	v_add_f32_e32 v11, 1.0, v13
	v_rcp_f32_e32 v9, v9
	v_readlane_b32 s92, v254, 51
	s_waitcnt lgkmcnt(0)
	v_add_f32_e32 v13, v10, v14
	ds_bpermute_b32 v14, v212, v13
	v_rcp_f32_e32 v10, v11
	v_and_b32_e32 v11, 0xffff0000, v207
	v_mul_f32_e32 v11, 0xbfb8aa3b, v11
	v_exp_f32_e32 v11, v11
	s_waitcnt lgkmcnt(0)
	v_add_f32_e32 v13, v13, v14
	v_fmamk_f32 v13, v13, 0x3b800000, v225
	v_mul_f32_e32 v14, 0x4b800000, v13
	v_cmp_gt_f32_e32 vcc, s30, v13
	v_add_f32_e32 v11, 1.0, v11
	v_rcp_f32_e32 v11, v11
	v_cndmask_b32_e32 v13, v13, v14, vcc
	v_rsq_f32_e32 v13, v13
	v_pk_mul_f32 v[4:5], v[8:9], v[4:5]
	v_pk_mul_f32 v[2:3], v[10:11], v[2:3]
	v_readlane_b32 s96, v254, 52
	v_mul_f32_e32 v8, 0x45800000, v13
	v_cndmask_b32_e32 v8, v13, v8, vcc
	v_pk_mul_f32 v[4:5], v[4:5], v[8:9] op_sel_hi:[1,0]
	v_pk_mul_f32 v[2:3], v[2:3], v[8:9] op_sel_hi:[1,0]
	s_waitcnt vmcnt(0)
	v_pk_mul_f32 v[4:5], v[152:153], v[4:5]
	v_pk_mul_f32 v[2:3], v[154:155], v[2:3]
	v_cvt_pk_bf16_f32 v4, v4, v5
	v_cvt_pk_bf16_f32 v5, v2, v3
	v_add_u32_e32 v2, s3, v12
	global_store_dwordx2 v[6:7], v[4:5], off sc1
	s_nop 1
	ds_read_b64 v[4:5], v2
	v_and_b32_e32 v12, 0xffff0000, v204
	v_lshlrev_b32_e32 v13, 16, v205
	v_mul_f32_e32 v12, 0xbfb8aa3b, v12
	v_mul_f32_e32 v13, 0xbfb8aa3b, v13
	s_waitcnt lgkmcnt(0)
	v_and_b32_e32 v7, 0xffff0000, v5
	v_and_b32_e32 v9, 0xffff0000, v4
	v_lshlrev_b32_e32 v6, 16, v5
	v_lshlrev_b32_e32 v8, 16, v4
	v_mov_b32_e32 v10, v9
	v_mov_b32_e32 v11, v7
	v_mov_b32_e32 v4, v8
	v_mov_b32_e32 v5, v6
	v_pk_mul_f32 v[10:11], v[10:11], v[10:11]
	v_exp_f32_e32 v12, v12
	v_pk_fma_f32 v[4:5], v[4:5], v[4:5], v[10:11]
	v_exp_f32_e32 v13, v13
	v_add_f32_e32 v3, v4, v5
	ds_bpermute_b32 v4, v189, v3
	v_lshlrev_b32_e32 v5, 16, v204
	v_mul_f32_e32 v5, 0xbfb8aa3b, v5
	v_exp_f32_e32 v10, v5
	v_readlane_b32 s57, v255, 5
	s_waitcnt lgkmcnt(0)
	v_add_f32_e32 v3, v3, v4
	ds_bpermute_b32 v4, v191, v3
	v_add_f32_e32 v10, 1.0, v10
	v_rcp_f32_e32 v10, v10
	v_readlane_b32 s58, v255, 6
	v_readlane_b32 s59, v255, 7
	s_waitcnt lgkmcnt(0)
	v_add_f32_e32 v3, v3, v4
	ds_bpermute_b32 v11, v209, v3
	v_lshl_add_u64 v[4:5], v[0:1], 0, s[12:13]
	s_add_u32 s12, s2, s54
	s_addc_u32 s13, s19, 0
	s_lshl_b64 s[12:13], s[12:13], 11
	s_waitcnt lgkmcnt(0)
	v_add_f32_e32 v3, v3, v11
	ds_bpermute_b32 v11, v210, v3
	s_add_u32 s4, s2, s5
	s_addc_u32 s5, s19, 0
	s_lshl_b64 s[4:5], s[4:5], 11
	v_readlane_b32 s54, v254, 49
	s_waitcnt lgkmcnt(0)
	v_add_f32_e32 v3, v3, v11
	ds_bpermute_b32 v14, v211, v3
	v_add_f32_e32 v11, 1.0, v12
	v_add_f32_e32 v12, 1.0, v13
	v_rcp_f32_e32 v11, v11
	v_rcp_f32_e32 v12, v12
	s_waitcnt lgkmcnt(0)
	v_add_f32_e32 v3, v3, v14
	ds_bpermute_b32 v13, v212, v3
	v_and_b32_e32 v14, 0xffff0000, v205
	v_mul_f32_e32 v14, 0xbfb8aa3b, v14
	v_exp_f32_e32 v14, v14
	v_pk_mul_f32 v[8:9], v[10:11], v[8:9]
	s_waitcnt lgkmcnt(0)
	v_add_f32_e32 v3, v3, v13
	v_fmamk_f32 v3, v3, 0x3b800000, v225
	v_mul_f32_e32 v13, 0x4b800000, v3
	v_cmp_gt_f32_e32 vcc, s30, v3
	v_readlane_b32 s55, v254, 50
	v_readlane_b32 s63, v254, 53
	v_cndmask_b32_e32 v3, v3, v13, vcc
	v_rsq_f32_e32 v3, v3
	v_add_f32_e32 v13, 1.0, v14
	v_rcp_f32_e32 v13, v13
	v_mul_f32_e32 v10, 0x45800000, v3
	v_cndmask_b32_e32 v10, v3, v10, vcc
	v_pk_mul_f32 v[6:7], v[12:13], v[6:7]
	v_pk_mul_f32 v[8:9], v[8:9], v[10:11] op_sel_hi:[1,0]
	v_pk_mul_f32 v[6:7], v[6:7], v[10:11] op_sel_hi:[1,0]
	v_pk_mul_f32 v[8:9], v[152:153], v[8:9]
	v_pk_mul_f32 v[6:7], v[154:155], v[6:7]
	v_cvt_pk_bf16_f32 v8, v8, v9
	v_cvt_pk_bf16_f32 v9, v6, v7
	global_store_dwordx2 v[4:5], v[8:9], off sc1
	s_nop 1
	ds_read_b64 v[4:5], v2 offset:528
	v_and_b32_e32 v12, 0xffff0000, v202
	v_lshlrev_b32_e32 v13, 16, v203
	v_mul_f32_e32 v12, 0xbfb8aa3b, v12
	v_mul_f32_e32 v13, 0xbfb8aa3b, v13
	s_waitcnt lgkmcnt(0)
	v_and_b32_e32 v7, 0xffff0000, v5
	v_and_b32_e32 v9, 0xffff0000, v4
	v_lshlrev_b32_e32 v6, 16, v5
	v_lshlrev_b32_e32 v8, 16, v4
	v_mov_b32_e32 v10, v9
	v_mov_b32_e32 v11, v7
	v_mov_b32_e32 v4, v8
	v_mov_b32_e32 v5, v6
	v_pk_mul_f32 v[10:11], v[10:11], v[10:11]
	v_exp_f32_e32 v12, v12
	v_pk_fma_f32 v[4:5], v[4:5], v[4:5], v[10:11]
	v_exp_f32_e32 v13, v13
	v_add_f32_e32 v3, v4, v5
	ds_bpermute_b32 v4, v189, v3
	v_lshlrev_b32_e32 v5, 16, v202
	v_mul_f32_e32 v5, 0xbfb8aa3b, v5
	v_exp_f32_e32 v10, v5
	s_waitcnt lgkmcnt(0)
	v_add_f32_e32 v3, v3, v4
	ds_bpermute_b32 v4, v191, v3
	v_add_f32_e32 v10, 1.0, v10
	v_rcp_f32_e32 v10, v10
	s_waitcnt lgkmcnt(0)
	v_add_f32_e32 v3, v3, v4
	ds_bpermute_b32 v11, v209, v3
	v_lshl_add_u64 v[4:5], v[0:1], 0, s[12:13]
	s_waitcnt lgkmcnt(0)
	v_add_f32_e32 v3, v3, v11
	ds_bpermute_b32 v11, v210, v3
	s_waitcnt lgkmcnt(0)
	v_add_f32_e32 v3, v3, v11
	ds_bpermute_b32 v14, v211, v3
	v_add_f32_e32 v11, 1.0, v12
	v_add_f32_e32 v12, 1.0, v13
	v_rcp_f32_e32 v11, v11
	v_rcp_f32_e32 v12, v12
	s_waitcnt lgkmcnt(0)
	v_add_f32_e32 v3, v3, v14
	ds_bpermute_b32 v13, v212, v3
	v_and_b32_e32 v14, 0xffff0000, v203
	v_mul_f32_e32 v14, 0xbfb8aa3b, v14
	v_exp_f32_e32 v14, v14
	v_pk_mul_f32 v[8:9], v[10:11], v[8:9]
	s_waitcnt lgkmcnt(0)
	v_add_f32_e32 v3, v3, v13
	v_fmamk_f32 v3, v3, 0x3b800000, v225
	v_mul_f32_e32 v13, 0x4b800000, v3
	v_cmp_gt_f32_e32 vcc, s30, v3
	s_nop 1
	v_cndmask_b32_e32 v3, v3, v13, vcc
	v_rsq_f32_e32 v3, v3
	v_add_f32_e32 v13, 1.0, v14
	v_rcp_f32_e32 v13, v13
	v_mul_f32_e32 v10, 0x45800000, v3
	v_cndmask_b32_e32 v10, v3, v10, vcc
	v_pk_mul_f32 v[6:7], v[12:13], v[6:7]
	v_pk_mul_f32 v[8:9], v[8:9], v[10:11] op_sel_hi:[1,0]
	v_pk_mul_f32 v[6:7], v[6:7], v[10:11] op_sel_hi:[1,0]
	v_pk_mul_f32 v[8:9], v[152:153], v[8:9]
	v_pk_mul_f32 v[6:7], v[154:155], v[6:7]
	v_cvt_pk_bf16_f32 v8, v8, v9
	v_cvt_pk_bf16_f32 v9, v6, v7
	global_store_dwordx2 v[4:5], v[8:9], off sc1
	s_nop 1
	ds_read_b64 v[4:5], v2 offset:1056
	v_and_b32_e32 v12, 0xffff0000, v200
	v_lshlrev_b32_e32 v13, 16, v201
	v_mul_f32_e32 v12, 0xbfb8aa3b, v12
	v_mul_f32_e32 v13, 0xbfb8aa3b, v13
	s_waitcnt lgkmcnt(0)
	v_and_b32_e32 v7, 0xffff0000, v5
	v_and_b32_e32 v9, 0xffff0000, v4
	v_lshlrev_b32_e32 v6, 16, v5
	v_lshlrev_b32_e32 v8, 16, v4
	v_mov_b32_e32 v10, v9
	v_mov_b32_e32 v11, v7
	v_mov_b32_e32 v4, v8
	v_mov_b32_e32 v5, v6
	v_pk_mul_f32 v[10:11], v[10:11], v[10:11]
	v_exp_f32_e32 v12, v12
	v_pk_fma_f32 v[4:5], v[4:5], v[4:5], v[10:11]
	v_exp_f32_e32 v13, v13
	v_add_f32_e32 v3, v4, v5
	ds_bpermute_b32 v4, v189, v3
	v_lshlrev_b32_e32 v5, 16, v200
	v_mul_f32_e32 v5, 0xbfb8aa3b, v5
	v_exp_f32_e32 v10, v5
	s_waitcnt lgkmcnt(0)
	v_add_f32_e32 v3, v3, v4
	ds_bpermute_b32 v4, v191, v3
	v_add_f32_e32 v10, 1.0, v10
	v_rcp_f32_e32 v10, v10
	s_waitcnt lgkmcnt(0)
	v_add_f32_e32 v3, v3, v4
	ds_bpermute_b32 v11, v209, v3
	v_lshl_add_u64 v[4:5], v[0:1], 0, s[4:5]
	s_add_u32 s4, s2, s36
	s_addc_u32 s5, s19, 0
	s_lshl_b64 s[4:5], s[4:5], 11
	s_waitcnt lgkmcnt(0)
	v_add_f32_e32 v3, v3, v11
	ds_bpermute_b32 v11, v210, v3
	s_waitcnt lgkmcnt(0)
	v_add_f32_e32 v3, v3, v11
	ds_bpermute_b32 v14, v211, v3
	v_add_f32_e32 v11, 1.0, v12
	v_add_f32_e32 v12, 1.0, v13
	v_rcp_f32_e32 v11, v11
	v_rcp_f32_e32 v12, v12
	s_waitcnt lgkmcnt(0)
	v_add_f32_e32 v3, v3, v14
	ds_bpermute_b32 v13, v212, v3
	v_and_b32_e32 v14, 0xffff0000, v201
	v_mul_f32_e32 v14, 0xbfb8aa3b, v14
	v_exp_f32_e32 v14, v14
	v_pk_mul_f32 v[8:9], v[10:11], v[8:9]
	s_waitcnt lgkmcnt(0)
	v_add_f32_e32 v3, v3, v13
	v_fmamk_f32 v3, v3, 0x3b800000, v225
	v_mul_f32_e32 v13, 0x4b800000, v3
	v_cmp_gt_f32_e32 vcc, s30, v3
	s_nop 1
	v_cndmask_b32_e32 v3, v3, v13, vcc
	v_rsq_f32_e32 v3, v3
	v_add_f32_e32 v13, 1.0, v14
	v_rcp_f32_e32 v13, v13
	v_mul_f32_e32 v10, 0x45800000, v3
	v_cndmask_b32_e32 v10, v3, v10, vcc
	v_pk_mul_f32 v[6:7], v[12:13], v[6:7]
	v_pk_mul_f32 v[8:9], v[8:9], v[10:11] op_sel_hi:[1,0]
	v_pk_mul_f32 v[6:7], v[6:7], v[10:11] op_sel_hi:[1,0]
	v_pk_mul_f32 v[8:9], v[152:153], v[8:9]
	v_pk_mul_f32 v[6:7], v[154:155], v[6:7]
	v_cvt_pk_bf16_f32 v8, v8, v9
	v_cvt_pk_bf16_f32 v9, v6, v7
	global_store_dwordx2 v[4:5], v[8:9], off sc1
	s_nop 1
	ds_read_b64 v[4:5], v2 offset:1584
	v_and_b32_e32 v12, 0xffff0000, v198
	v_lshlrev_b32_e32 v13, 16, v199
	v_mul_f32_e32 v12, 0xbfb8aa3b, v12
	v_mul_f32_e32 v13, 0xbfb8aa3b, v13
	s_waitcnt lgkmcnt(0)
	v_and_b32_e32 v7, 0xffff0000, v5
	v_and_b32_e32 v9, 0xffff0000, v4
	v_lshlrev_b32_e32 v6, 16, v5
	v_lshlrev_b32_e32 v8, 16, v4
	v_mov_b32_e32 v10, v9
	v_mov_b32_e32 v11, v7
	v_mov_b32_e32 v4, v8
	v_mov_b32_e32 v5, v6
	v_pk_mul_f32 v[10:11], v[10:11], v[10:11]
	v_exp_f32_e32 v12, v12
	v_pk_fma_f32 v[4:5], v[4:5], v[4:5], v[10:11]
	v_exp_f32_e32 v13, v13
	v_add_f32_e32 v3, v4, v5
	ds_bpermute_b32 v4, v189, v3
	v_lshlrev_b32_e32 v5, 16, v198
	v_mul_f32_e32 v5, 0xbfb8aa3b, v5
	v_exp_f32_e32 v10, v5
	s_waitcnt lgkmcnt(0)
	v_add_f32_e32 v3, v3, v4
	ds_bpermute_b32 v4, v191, v3
	v_add_f32_e32 v10, 1.0, v10
	v_rcp_f32_e32 v10, v10
	s_waitcnt lgkmcnt(0)
	v_add_f32_e32 v3, v3, v4
	ds_bpermute_b32 v11, v209, v3
	v_lshl_add_u64 v[4:5], v[0:1], 0, s[4:5]
	s_add_u32 s4, s2, s35
	s_addc_u32 s5, s19, 0
	s_lshl_b64 s[4:5], s[4:5], 11
	s_waitcnt lgkmcnt(0)
	v_add_f32_e32 v3, v3, v11
	ds_bpermute_b32 v11, v210, v3
	v_readlane_b32 s34, v255, 11
	v_readlane_b32 s35, v255, 12
	s_waitcnt lgkmcnt(0)
	v_add_f32_e32 v3, v3, v11
	ds_bpermute_b32 v14, v211, v3
	v_add_f32_e32 v11, 1.0, v12
	v_add_f32_e32 v12, 1.0, v13
	v_rcp_f32_e32 v11, v11
	v_rcp_f32_e32 v12, v12
	s_waitcnt lgkmcnt(0)
	v_add_f32_e32 v3, v3, v14
	ds_bpermute_b32 v13, v212, v3
	v_and_b32_e32 v14, 0xffff0000, v199
	v_mul_f32_e32 v14, 0xbfb8aa3b, v14
	v_exp_f32_e32 v14, v14
	v_pk_mul_f32 v[8:9], v[10:11], v[8:9]
	s_waitcnt lgkmcnt(0)
	v_add_f32_e32 v3, v3, v13
	v_fmamk_f32 v3, v3, 0x3b800000, v225
	v_mul_f32_e32 v13, 0x4b800000, v3
	v_cmp_gt_f32_e32 vcc, s30, v3
	s_nop 1
	v_cndmask_b32_e32 v3, v3, v13, vcc
	v_rsq_f32_e32 v3, v3
	v_add_f32_e32 v13, 1.0, v14
	v_rcp_f32_e32 v13, v13
	v_mul_f32_e32 v10, 0x45800000, v3
	v_cndmask_b32_e32 v10, v3, v10, vcc
	v_pk_mul_f32 v[6:7], v[12:13], v[6:7]
	v_pk_mul_f32 v[8:9], v[8:9], v[10:11] op_sel_hi:[1,0]
	v_pk_mul_f32 v[6:7], v[6:7], v[10:11] op_sel_hi:[1,0]
	v_pk_mul_f32 v[8:9], v[152:153], v[8:9]
	v_pk_mul_f32 v[6:7], v[154:155], v[6:7]
	v_cvt_pk_bf16_f32 v8, v8, v9
	v_cvt_pk_bf16_f32 v9, v6, v7
	global_store_dwordx2 v[4:5], v[8:9], off sc1
	s_nop 1
	ds_read_b64 v[4:5], v2 offset:2112
	v_and_b32_e32 v12, 0xffff0000, v196
	v_lshlrev_b32_e32 v13, 16, v197
	v_mul_f32_e32 v12, 0xbfb8aa3b, v12
	v_mul_f32_e32 v13, 0xbfb8aa3b, v13
	s_waitcnt lgkmcnt(0)
	v_and_b32_e32 v7, 0xffff0000, v5
	v_and_b32_e32 v9, 0xffff0000, v4
	v_lshlrev_b32_e32 v6, 16, v5
	v_lshlrev_b32_e32 v8, 16, v4
	v_mov_b32_e32 v10, v9
	v_mov_b32_e32 v11, v7
	v_mov_b32_e32 v4, v8
	v_mov_b32_e32 v5, v6
	v_pk_mul_f32 v[10:11], v[10:11], v[10:11]
	v_exp_f32_e32 v12, v12
	v_pk_fma_f32 v[4:5], v[4:5], v[4:5], v[10:11]
	v_exp_f32_e32 v13, v13
	v_add_f32_e32 v3, v4, v5
	ds_bpermute_b32 v4, v189, v3
	v_lshlrev_b32_e32 v5, 16, v196
	v_mul_f32_e32 v5, 0xbfb8aa3b, v5
	v_exp_f32_e32 v10, v5
	s_waitcnt lgkmcnt(0)
	v_add_f32_e32 v3, v3, v4
	ds_bpermute_b32 v4, v191, v3
	v_add_f32_e32 v10, 1.0, v10
	v_rcp_f32_e32 v10, v10
	s_waitcnt lgkmcnt(0)
	v_add_f32_e32 v3, v3, v4
	ds_bpermute_b32 v11, v209, v3
	v_lshl_add_u64 v[4:5], v[0:1], 0, s[4:5]
	s_add_u32 s4, s2, s21
	s_addc_u32 s5, s19, 0
	s_lshl_b64 s[4:5], s[4:5], 11
	s_waitcnt lgkmcnt(0)
	v_add_f32_e32 v3, v3, v11
	ds_bpermute_b32 v11, v210, v3
	s_add_u32 s2, s2, s20
	s_addc_u32 s3, s19, 0
	s_lshl_b64 s[2:3], s[2:3], 11
	s_waitcnt lgkmcnt(0)
	v_add_f32_e32 v3, v3, v11
	ds_bpermute_b32 v14, v211, v3
	v_add_f32_e32 v11, 1.0, v12
	v_add_f32_e32 v12, 1.0, v13
	v_rcp_f32_e32 v11, v11
	v_rcp_f32_e32 v12, v12
	s_waitcnt lgkmcnt(0)
	v_add_f32_e32 v3, v3, v14
	ds_bpermute_b32 v13, v212, v3
	v_and_b32_e32 v14, 0xffff0000, v197
	v_mul_f32_e32 v14, 0xbfb8aa3b, v14
	v_exp_f32_e32 v14, v14
	v_pk_mul_f32 v[8:9], v[10:11], v[8:9]
	s_waitcnt lgkmcnt(0)
	v_add_f32_e32 v3, v3, v13
	v_fmamk_f32 v3, v3, 0x3b800000, v225
	v_mul_f32_e32 v13, 0x4b800000, v3
	v_cmp_gt_f32_e32 vcc, s30, v3
	s_nop 1
	v_cndmask_b32_e32 v3, v3, v13, vcc
	v_rsq_f32_e32 v3, v3
	v_add_f32_e32 v13, 1.0, v14
	v_rcp_f32_e32 v13, v13
	v_mul_f32_e32 v10, 0x45800000, v3
	v_cndmask_b32_e32 v10, v3, v10, vcc
	v_pk_mul_f32 v[6:7], v[12:13], v[6:7]
	v_pk_mul_f32 v[8:9], v[8:9], v[10:11] op_sel_hi:[1,0]
	v_pk_mul_f32 v[6:7], v[6:7], v[10:11] op_sel_hi:[1,0]
	v_pk_mul_f32 v[8:9], v[152:153], v[8:9]
	v_pk_mul_f32 v[6:7], v[154:155], v[6:7]
	v_cvt_pk_bf16_f32 v8, v8, v9
	v_cvt_pk_bf16_f32 v9, v6, v7
	global_store_dwordx2 v[4:5], v[8:9], off sc1
	s_nop 1
	ds_read_b64 v[4:5], v2 offset:2640
	v_and_b32_e32 v12, 0xffff0000, v194
	v_lshlrev_b32_e32 v13, 16, v195
	v_mul_f32_e32 v12, 0xbfb8aa3b, v12
	v_mul_f32_e32 v13, 0xbfb8aa3b, v13
	s_waitcnt lgkmcnt(0)
	v_and_b32_e32 v7, 0xffff0000, v5
	v_and_b32_e32 v9, 0xffff0000, v4
	v_lshlrev_b32_e32 v6, 16, v5
	v_lshlrev_b32_e32 v8, 16, v4
	v_mov_b32_e32 v10, v9
	v_mov_b32_e32 v11, v7
	v_mov_b32_e32 v4, v8
	v_mov_b32_e32 v5, v6
	v_pk_mul_f32 v[10:11], v[10:11], v[10:11]
	v_exp_f32_e32 v12, v12
	v_pk_fma_f32 v[4:5], v[4:5], v[4:5], v[10:11]
	v_exp_f32_e32 v13, v13
	v_add_f32_e32 v3, v4, v5
	ds_bpermute_b32 v4, v189, v3
	v_lshlrev_b32_e32 v5, 16, v194
	v_mul_f32_e32 v5, 0xbfb8aa3b, v5
	v_exp_f32_e32 v10, v5
	s_waitcnt lgkmcnt(0)
	v_add_f32_e32 v3, v3, v4
	ds_bpermute_b32 v4, v191, v3
	v_add_f32_e32 v10, 1.0, v10
	v_rcp_f32_e32 v10, v10
	s_waitcnt lgkmcnt(0)
	v_add_f32_e32 v3, v3, v4
	ds_bpermute_b32 v11, v209, v3
	v_lshl_add_u64 v[4:5], v[0:1], 0, s[4:5]
	v_lshl_add_u64 v[0:1], v[0:1], 0, s[2:3]
	s_waitcnt lgkmcnt(0)
	v_add_f32_e32 v3, v3, v11
	ds_bpermute_b32 v11, v210, v3
	s_waitcnt lgkmcnt(0)
	v_add_f32_e32 v3, v3, v11
	ds_bpermute_b32 v14, v211, v3
	v_add_f32_e32 v11, 1.0, v12
	v_add_f32_e32 v12, 1.0, v13
	v_rcp_f32_e32 v11, v11
	v_rcp_f32_e32 v12, v12
	s_waitcnt lgkmcnt(0)
	v_add_f32_e32 v3, v3, v14
	ds_bpermute_b32 v13, v212, v3
	v_and_b32_e32 v14, 0xffff0000, v195
	v_mul_f32_e32 v14, 0xbfb8aa3b, v14
	v_exp_f32_e32 v14, v14
	v_pk_mul_f32 v[8:9], v[10:11], v[8:9]
	s_waitcnt lgkmcnt(0)
	v_add_f32_e32 v3, v3, v13
	v_fmamk_f32 v3, v3, 0x3b800000, v225
	v_mul_f32_e32 v13, 0x4b800000, v3
	v_cmp_gt_f32_e32 vcc, s30, v3
	s_nop 1
	v_cndmask_b32_e32 v3, v3, v13, vcc
	v_rsq_f32_e32 v3, v3
	v_add_f32_e32 v13, 1.0, v14
	v_rcp_f32_e32 v13, v13
	v_mul_f32_e32 v10, 0x45800000, v3
	v_cndmask_b32_e32 v10, v3, v10, vcc
	v_pk_mul_f32 v[6:7], v[12:13], v[6:7]
	v_pk_mul_f32 v[8:9], v[8:9], v[10:11] op_sel_hi:[1,0]
	v_pk_mul_f32 v[6:7], v[6:7], v[10:11] op_sel_hi:[1,0]
	v_pk_mul_f32 v[8:9], v[152:153], v[8:9]
	v_pk_mul_f32 v[6:7], v[154:155], v[6:7]
	v_cvt_pk_bf16_f32 v8, v8, v9
	v_cvt_pk_bf16_f32 v9, v6, v7
	global_store_dwordx2 v[4:5], v[8:9], off sc1
	s_nop 1
	ds_read_b64 v[2:3], v2 offset:3168
	v_lshlrev_b32_e32 v10, 16, v193
	v_mul_f32_e32 v10, 0xbfb8aa3b, v10
	v_exp_f32_e32 v10, v10
	s_waitcnt lgkmcnt(0)
	v_and_b32_e32 v5, 0xffff0000, v3
	v_and_b32_e32 v7, 0xffff0000, v2
	v_lshlrev_b32_e32 v4, 16, v3
	v_lshlrev_b32_e32 v6, 16, v2
	v_mov_b32_e32 v8, v7
	v_mov_b32_e32 v9, v5
	v_mov_b32_e32 v2, v6
	v_mov_b32_e32 v3, v4
	v_pk_mul_f32 v[8:9], v[8:9], v[8:9]
	s_nop 0
	v_pk_fma_f32 v[2:3], v[2:3], v[2:3], v[8:9]
	v_lshlrev_b32_e32 v8, 16, v192
	v_add_f32_e32 v2, v2, v3
	ds_bpermute_b32 v3, v189, v2
	v_and_b32_e32 v9, 0xffff0000, v192
	v_mul_f32_e32 v8, 0xbfb8aa3b, v8
	v_mul_f32_e32 v9, 0xbfb8aa3b, v9
	v_exp_f32_e32 v8, v8
	s_waitcnt lgkmcnt(0)
	v_add_f32_e32 v2, v2, v3
	ds_bpermute_b32 v3, v191, v2
	v_exp_f32_e32 v9, v9
	v_add_f32_e32 v8, 1.0, v8
	s_waitcnt lgkmcnt(0)
	v_add_f32_e32 v2, v2, v3
	ds_bpermute_b32 v3, v209, v2
	s_waitcnt lgkmcnt(0)
	v_add_f32_e32 v2, v2, v3
	ds_bpermute_b32 v3, v210, v2
	s_waitcnt lgkmcnt(0)
	v_add_f32_e32 v11, v2, v3
	ds_bpermute_b32 v12, v211, v11
	v_add_f32_e32 v3, 1.0, v9
	v_rcp_f32_e32 v2, v8
	v_add_f32_e32 v8, 1.0, v10
	v_rcp_f32_e32 v3, v3
	s_waitcnt lgkmcnt(0)
	v_add_f32_e32 v9, v11, v12
	ds_bpermute_b32 v10, v212, v9
	v_and_b32_e32 v11, 0xffff0000, v193
	v_mul_f32_e32 v11, 0xbfb8aa3b, v11
	v_exp_f32_e32 v11, v11
	v_rcp_f32_e32 v8, v8
	s_waitcnt lgkmcnt(0)
	v_add_f32_e32 v9, v9, v10
	v_fmamk_f32 v9, v9, 0x3b800000, v225
	v_mul_f32_e32 v10, 0x4b800000, v9
	v_cmp_gt_f32_e32 vcc, s30, v9
	v_pk_mul_f32 v[2:3], v[2:3], v[6:7]
	s_nop 0
	v_cndmask_b32_e32 v9, v9, v10, vcc
	v_rsq_f32_e32 v10, v9
	v_add_f32_e32 v9, 1.0, v11
	v_rcp_f32_e32 v9, v9
	v_mul_f32_e32 v6, 0x45800000, v10
	v_cndmask_b32_e32 v6, v10, v6, vcc
	v_pk_mul_f32 v[4:5], v[8:9], v[4:5]
	v_pk_mul_f32 v[2:3], v[2:3], v[6:7] op_sel_hi:[1,0]
	v_pk_mul_f32 v[4:5], v[4:5], v[6:7] op_sel_hi:[1,0]
	v_pk_mul_f32 v[2:3], v[152:153], v[2:3]
	v_pk_mul_f32 v[4:5], v[154:155], v[4:5]
	v_cvt_pk_bf16_f32 v2, v2, v3
	v_cvt_pk_bf16_f32 v3, v4, v5
	global_store_dwordx2 v[0:1], v[2:3], off sc1
	s_nop 1
	s_barrier

.LBB0_205:
	s_lshl_b32 s63, s12, 3
	s_lshl_b32 s3, s62, 1
	v_readlane_b32 s5, v252, 58
	s_add_u32 s46, s5, s3
	v_readlane_b32 s3, v252, 59
	s_addc_u32 s47, s3, 0
	s_lshr_b32 s13, s2, 7
	s_lshl_b32 s2, s12, 1
	s_and_b32 s14, s2, 2
	s_lshl_b32 s17, s13, 4
	s_lshl_b32 s2, s62, 2
	s_add_u32 s50, s68, s2
	s_addc_u32 s51, s69, 0
	s_add_i32 s2, s90, 0
	s_lshl_b32 s11, s12, 5
	s_add_i32 s2, s2, 0x18400
	s_or_b32 s92, s63, 1
	s_or_b32 s54, s63, 2
	s_or_b32 s5, s63, 3
	s_or_b32 s36, s63, 4
	s_or_b32 s35, s63, 5
	s_or_b32 s21, s63, 6
	s_or_b32 s20, s63, 7
	s_cmp_le_u32 s14, s13
	s_cselect_b64 s[52:53], -1, 0
	s_lshl_b32 s58, s14, 4
	s_lshl_b32 s59, s14, 5
	s_or_b32 s15, s14, 1
	s_cmp_ge_u32 s14, s13
	s_mov_b32 s13, s37
	s_mul_i32 s16, s12, 0x1080
	s_cselect_b64 s[90:91], -1, 0
	s_lshl_b32 s96, s15, 5
	s_lshl_b32 s97, s15, 4
	s_lshl_b64 s[14:15], s[82:83], 22
	s_lshl_b64 s[12:13], s[12:13], 14
	s_add_u32 s12, s14, s12
	s_addc_u32 s31, s15, s13
	s_lshl_b32 s4, s4, 9
	s_or_b32 s4, s12, s4
	s_lshl_b64 s[12:13], s[82:83], 12
	s_add_i32 s56, 0, 0x21800
	s_add_u32 s57, s12, 0xb000080
	v_mov_b32_e32 v0, 0
	s_mul_i32 s3, s92, 0x210
	s_addc_u32 s14, s13, 0
	s_mov_b64 s[82:83], 0
	v_mov_b32_e32 v1, v0
	v_mov_b32_e32 v2, v0
	v_mov_b32_e32 v3, v0
	v_mov_b32_e32 v4, v0
	v_mov_b32_e32 v5, v0
	v_mov_b32_e32 v6, v0
	v_mov_b32_e32 v7, v0
	v_mov_b32_e32 v8, v0
	v_mov_b32_e32 v9, v0
	v_mov_b32_e32 v10, v0
	v_mov_b32_e32 v11, v0
	v_mov_b32_e32 v12, v0
	v_mov_b32_e32 v13, v0
	v_mov_b32_e32 v14, v0
	v_mov_b32_e32 v15, v0
	v_mov_b32_e32 v16, v0
	v_mov_b32_e32 v17, v0
	v_mov_b32_e32 v18, v0
	v_mov_b32_e32 v19, v0
	v_mov_b32_e32 v20, v0
	v_mov_b32_e32 v21, v0
	v_mov_b32_e32 v22, v0
	v_mov_b32_e32 v23, v0
	v_mov_b32_e32 v24, v0
	v_mov_b32_e32 v25, v0
	v_mov_b32_e32 v26, v0
	v_mov_b32_e32 v27, v0
	v_mov_b32_e32 v28, v0
	v_mov_b32_e32 v29, v0
	v_mov_b32_e32 v30, v0
	v_mov_b32_e32 v31, v0
	v_mov_b32_e32 v32, v0
	v_mov_b32_e32 v33, v0
	v_mov_b32_e32 v34, v0
	v_mov_b32_e32 v35, v0
	v_mov_b32_e32 v36, v0
	v_mov_b32_e32 v37, v0
	v_mov_b32_e32 v38, v0
	v_mov_b32_e32 v39, v0
	v_mov_b32_e32 v40, v0
	v_mov_b32_e32 v41, v0
	v_mov_b32_e32 v42, v0
	v_mov_b32_e32 v43, v0
	v_mov_b32_e32 v44, v0
	v_mov_b32_e32 v45, v0
	v_mov_b32_e32 v46, v0
	v_mov_b32_e32 v47, v0
	v_mov_b32_e32 v48, v0
	v_mov_b32_e32 v49, v0
	v_mov_b32_e32 v50, v0
	v_mov_b32_e32 v51, v0
	v_mov_b32_e32 v52, v0
	v_mov_b32_e32 v53, v0
	v_mov_b32_e32 v54, v0
	v_mov_b32_e32 v55, v0
	v_mov_b32_e32 v56, v0
	v_mov_b32_e32 v57, v0
	v_mov_b32_e32 v58, v0
	v_mov_b32_e32 v59, v0
	v_mov_b32_e32 v60, v0
	v_mov_b32_e32 v61, v0
	v_mov_b32_e32 v62, v0
	v_mov_b32_e32 v63, v0
	v_and_b32_e32 v152, 63, v222
	v_lshlrev_b32_e32 v152, 4, v152
	global_load_dwordx4 v[152:155], v152, s[50:51]
	s_waitcnt vmcnt(0)
	s_branch .LBB0_207

.LBB0_207:
	v_mov_b32_e32 v214, v222
	v_mov_b32_e32 v64, s56
	ds_read2_b32 v[164:165], v64 offset0:32 offset1:64
	v_cndmask_b32_e64 v64, 0, 1, s[48:49]
	v_cmp_ne_u32_e64 s[42:43], 1, v64
	s_andn2_b64 vcc, exec, s[48:49]
	v_and_b32_e32 v168, 63, v214
	s_cbranch_vccnz .LBB0_211
	v_mov_b32_e32 v64, s56
	ds_read_b32 v64, v64
	v_lshl_add_u32 v67, v168, 2, 0
	s_waitcnt vmcnt(12) lgkmcnt(2)
	v_add_f32_e32 v66, v213, v98
	v_add_u32_e32 v68, 0x20800, v67
	ds_write_b32 v68, v213
	s_waitcnt lgkmcnt(1)
	v_add_f32_e32 v65, v213, v64
	v_max_f32_e32 v66, v65, v66
	v_add_u32_e32 v68, 0x20900, v67
	ds_write_b32 v68, v99
	v_add_u32_e32 v68, 0x20a00, v67
	v_sub_f32_e32 v65, v65, v66
	ds_write_b32 v68, v66
	v_mul_f32_e32 v68, 0x3fb8aa3b, v65
	v_fma_f32 v69, v65, s0, -v68
	v_rndne_f32_e32 v70, v68
	v_fmac_f32_e32 v69, 0x32a5705f, v65
	v_sub_f32_e32 v68, v68, v70
	v_add_f32_e32 v68, v68, v69
	v_exp_f32_e32 v68, v68
	v_cvt_i32_f32_e32 v69, v70
	v_cmp_ngt_f32_e32 vcc, s28, v65
	v_ldexp_f32 v68, v68, v69
	s_nop 0
	v_cndmask_b32_e32 v68, 0, v68, vcc
	v_cmp_nlt_f32_e32 vcc, s29, v65
	s_nop 1
	v_cndmask_b32_e32 v65, v229, v68, vcc
	v_add_u32_e32 v68, 0x20b00, v67
	ds_write_b32 v68, v65
	v_mul_f32_e32 v65, 0xbfb8aa3b, v66
	v_fma_f32 v68, v66, s94, -v65
	v_rndne_f32_e32 v69, v65
	v_fmac_f32_e32 v68, 0xb2a5705f, v66
	v_sub_f32_e32 v65, v65, v69
	v_add_f32_e32 v65, v65, v68
	v_exp_f32_e32 v65, v65
	v_cvt_i32_f32_e32 v68, v69
	v_cmp_nlt_f32_e32 vcc, s22, v66
	v_ldexp_f32 v65, v65, v68
	s_nop 0
	v_cndmask_b32_e32 v65, 0, v65, vcc
	v_cmp_ngt_f32_e32 vcc, s23, v66
	v_add_u32_e32 v66, 0x20f00, v67
	s_nop 0
	v_cndmask_b32_e32 v65, v229, v65, vcc
	v_cmp_eq_u32_e32 vcc, 0, v168
	ds_write_b32 v66, v65
	s_and_saveexec_b64 s[12:13], vcc
	s_cbranch_execz .LBB0_210
	v_add_f32_e32 v64, v165, v64
	v_sub_f32_e32 v64, v64, v164
	v_mul_f32_e32 v65, 0x3fb8aa3b, v64
	v_fma_f32 v66, v64, s0, -v65
	v_rndne_f32_e32 v67, v65
	v_fmac_f32_e32 v66, 0x32a5705f, v64
	v_sub_f32_e32 v65, v65, v67
	v_add_f32_e32 v65, v65, v66
	v_cvt_i32_f32_e32 v66, v67
	v_exp_f32_e32 v65, v65
	v_cmp_ngt_f32_e32 vcc, s28, v64
	v_ldexp_f32 v65, v65, v66
	s_nop 0
	v_cndmask_b32_e32 v65, 0, v65, vcc
	v_cmp_nlt_f32_e32 vcc, s29, v64
	s_nop 1
	v_cndmask_b32_e32 v64, v229, v65, vcc
	v_mov_b32_e32 v65, s10
	ds_write_b32 v65, v64

.LBB0_211:
	v_and_b32_e32 v215, 31, v214
	v_lshlrev_b32_e32 v64, 3, v215
	v_add_u32_e32 v65, s33, v64
	v_or_b32_e32 v64, s55, v64
	v_cmp_lt_u32_e64 s[44:45], 15, v215
	s_movk_i32 s12, 0x2000
	s_waitcnt vmcnt(12)
	v_lshlrev_b32_e32 v166, 16, v104
	v_cndmask_b32_e64 v169, v64, v65, s[44:45]
	v_lshlrev_b32_e32 v96, 2, v169
	v_lshlrev_b32_e32 v171, 4, v215
	v_add_u32_e32 v171, 0x21a00, v171
	v_and_b32_e32 v167, 0xffff0000, v104
	s_mov_b64 s[12:13], 0x3000
	ds_read_b128 v[84:87], v171 offset:1024
	ds_read_b128 v[88:91], v171
	ds_read_b128 v[92:95], v171 offset:4096
	ds_read_b128 v[156:159], v171 offset:2048
	ds_read_b128 v[160:163], v171 offset:3072
	ds_read_b128 v[64:67], v171 offset:512
	ds_read_b128 v[68:71], v171 offset:4608
	ds_read_b128 v[72:75], v171 offset:1536
	ds_read_b128 v[76:79], v171 offset:2560
	ds_read_b128 v[80:83], v171 offset:3584
	v_lshlrev_b32_e32 v172, 16, v100
	v_and_b32_e32 v173, 0xffff0000, v100
	v_lshlrev_b32_e32 v174, 16, v108
	v_and_b32_e32 v175, 0xffff0000, v108
	v_lshlrev_b32_e32 v176, 16, v112
	v_and_b32_e32 v177, 0xffff0000, v112
	v_lshlrev_b32_e32 v178, 16, v116
	v_and_b32_e32 v179, 0xffff0000, v116
	v_lshlrev_b32_e32 v180, 16, v120
	v_and_b32_e32 v181, 0xffff0000, v120
	v_lshlrev_b32_e32 v182, 16, v124
	v_and_b32_e32 v183, 0xffff0000, v124
	v_ashrrev_i32_e32 v170, 5, v214
	s_movk_i32 s12, 0x440
	v_cmp_gt_u32_e32 vcc, 16, v215
	s_waitcnt lgkmcnt(7)
	v_pk_fma_f32 v[166:167], v[88:89], v[166:167], v[92:93]
	v_pk_fma_f32 v[184:185], v[88:89], v[172:173], v[92:93]
	v_pk_fma_f32 v[186:187], v[88:89], v[174:175], v[92:93]
	v_pk_fma_f32 v[88:89], v[88:89], v[176:177], v[92:93]
	v_pk_fma_f32 v[92:93], v[84:85], v[172:173], v[166:167]
	v_pk_fma_f32 v[166:167], v[84:85], v[174:175], v[184:185]
	v_pk_fma_f32 v[172:173], v[84:85], v[176:177], v[186:187]
	v_pk_fma_f32 v[84:85], v[84:85], v[178:179], v[88:89]
	s_waitcnt lgkmcnt(6)
	v_pk_fma_f32 v[88:89], v[156:157], v[174:175], v[92:93]
	v_pk_fma_f32 v[92:93], v[156:157], v[176:177], v[166:167]
	v_pk_fma_f32 v[166:167], v[156:157], v[178:179], v[172:173]
	v_pk_fma_f32 v[84:85], v[156:157], v[180:181], v[84:85]
	s_waitcnt lgkmcnt(5)
	v_pk_fma_f32 v[88:89], v[160:161], v[176:177], v[88:89]
	v_pk_fma_f32 v[156:157], v[160:161], v[178:179], v[92:93]
	v_pk_fma_f32 v[166:167], v[160:161], v[180:181], v[166:167]
	v_pk_fma_f32 v[160:161], v[160:161], v[182:183], v[84:85]
	v_mul_f32_e32 v84, 0xbfb8aa3b, v88
	v_mul_f32_e32 v85, 0xbfb8aa3b, v89
	v_mul_f32_e32 v92, 0xbfb8aa3b, v156
	v_mul_f32_e32 v93, 0xbfb8aa3b, v157
	v_mul_f32_e32 v96, 0xbfb8aa3b, v166
	v_mul_f32_e32 v171, 0xbfb8aa3b, v167
	v_mul_f32_e32 v172, 0xbfb8aa3b, v160
	v_mul_f32_e32 v173, 0xbfb8aa3b, v161
	v_exp_f32_e32 v84, v84
	v_exp_f32_e32 v85, v85
	v_exp_f32_e32 v92, v92
	v_exp_f32_e32 v93, v93
	v_exp_f32_e32 v96, v96
	v_exp_f32_e32 v171, v171
	v_exp_f32_e32 v172, v172
	v_exp_f32_e32 v173, v173
	v_add_f32_e32 v84, 1.0, v84
	v_add_f32_e32 v85, 1.0, v85
	v_add_f32_e32 v92, 1.0, v92
	v_add_f32_e32 v93, 1.0, v93
	v_add_f32_e32 v96, 1.0, v96
	v_add_f32_e32 v171, 1.0, v171
	v_add_f32_e32 v176, 1.0, v172
	v_add_f32_e32 v177, 1.0, v173
	v_rcp_f32_e32 v84, v84
	v_rcp_f32_e32 v85, v85
	v_rcp_f32_e32 v172, v92
	v_rcp_f32_e32 v173, v93
	v_rcp_f32_e32 v174, v96
	v_rcp_f32_e32 v175, v171
	v_pk_mul_f32 v[92:93], v[88:89], v[84:85]
	v_pk_mul_f32 v[88:89], v[156:157], v[172:173]
	v_lshlrev_b32_e32 v156, 16, v105
	v_and_b32_e32 v157, 0xffff0000, v105
	v_pk_mul_f32 v[84:85], v[166:167], v[174:175]
	v_lshlrev_b32_e32 v166, 16, v101
	v_and_b32_e32 v167, 0xffff0000, v101
	v_pk_fma_f32 v[156:157], v[90:91], v[156:157], v[94:95]
	v_lshlrev_b32_e32 v172, 16, v109
	v_and_b32_e32 v173, 0xffff0000, v109
	v_pk_fma_f32 v[156:157], v[86:87], v[166:167], v[156:157]
	v_lshlrev_b32_e32 v174, 16, v113
	v_and_b32_e32 v175, 0xffff0000, v113
	v_pk_fma_f32 v[156:157], v[158:159], v[172:173], v[156:157]
	v_rcp_f32_e32 v176, v176
	v_pk_fma_f32 v[178:179], v[162:163], v[174:175], v[156:157]
	v_rcp_f32_e32 v177, v177
	v_mul_f32_e32 v96, 0xbfb8aa3b, v178
	v_exp_f32_e32 v96, v96
	v_mul_f32_e32 v156, 0xbfb8aa3b, v179
	v_exp_f32_e32 v171, v156
	v_pk_fma_f32 v[166:167], v[90:91], v[166:167], v[94:95]
	v_pk_mul_f32 v[156:157], v[160:161], v[176:177]
	v_pk_fma_f32 v[166:167], v[86:87], v[172:173], v[166:167]
	v_add_f32_e32 v96, 1.0, v96
	v_lshlrev_b32_e32 v176, 16, v117
	v_and_b32_e32 v177, 0xffff0000, v117
	v_pk_fma_f32 v[166:167], v[158:159], v[174:175], v[166:167]
	v_rcp_f32_e32 v160, v96
	v_add_f32_e32 v96, 1.0, v171
	v_pk_fma_f32 v[166:167], v[162:163], v[176:177], v[166:167]
	v_rcp_f32_e32 v161, v96
	v_mul_f32_e32 v96, 0xbfb8aa3b, v166
	v_exp_f32_e32 v96, v96
	v_mul_f32_e32 v171, 0xbfb8aa3b, v167
	v_exp_f32_e32 v171, v171
	v_pk_fma_f32 v[172:173], v[90:91], v[172:173], v[94:95]
	v_add_f32_e32 v96, 1.0, v96
	v_pk_fma_f32 v[172:173], v[86:87], v[174:175], v[172:173]
	v_lshlrev_b32_e32 v180, 16, v121
	v_and_b32_e32 v181, 0xffff0000, v121
	v_pk_fma_f32 v[172:173], v[158:159], v[176:177], v[172:173]
	v_pk_mul_f32 v[160:161], v[178:179], v[160:161]
	v_rcp_f32_e32 v178, v96
	v_add_f32_e32 v96, 1.0, v171
	v_pk_fma_f32 v[172:173], v[162:163], v[180:181], v[172:173]
	v_rcp_f32_e32 v179, v96
	v_mul_f32_e32 v96, 0xbfb8aa3b, v172
	v_exp_f32_e32 v96, v96
	v_mul_f32_e32 v171, 0xbfb8aa3b, v173
	v_exp_f32_e32 v171, v171
	v_pk_fma_f32 v[90:91], v[90:91], v[174:175], v[94:95]
	v_add_f32_e32 v96, 1.0, v96
	v_pk_fma_f32 v[86:87], v[86:87], v[176:177], v[90:91]
	v_pk_mul_f32 v[166:167], v[166:167], v[178:179]
	v_rcp_f32_e32 v178, v96
	v_add_f32_e32 v96, 1.0, v171
	v_lshlrev_b32_e32 v182, 16, v125
	v_and_b32_e32 v183, 0xffff0000, v125
	v_pk_fma_f32 v[86:87], v[158:159], v[180:181], v[86:87]
	v_rcp_f32_e32 v179, v96
	v_pk_fma_f32 v[90:91], v[162:163], v[182:183], v[86:87]
	v_lshlrev_b32_e32 v158, 16, v106
	v_mul_f32_e32 v86, 0xbfb8aa3b, v90
	v_exp_f32_e32 v94, v86
	v_mul_f32_e32 v86, 0xbfb8aa3b, v91
	v_and_b32_e32 v159, 0xffff0000, v106
	v_exp_f32_e32 v95, v86
	v_lshlrev_b32_e32 v162, 16, v102
	v_and_b32_e32 v163, 0xffff0000, v102
	s_waitcnt lgkmcnt(3)
	v_pk_fma_f32 v[158:159], v[64:65], v[158:159], v[68:69]
	v_pk_mul_f32 v[86:87], v[172:173], v[178:179]
	v_lshlrev_b32_e32 v172, 16, v110
	v_and_b32_e32 v173, 0xffff0000, v110
	s_waitcnt lgkmcnt(2)
	v_pk_fma_f32 v[158:159], v[72:73], v[162:163], v[158:159]
	v_lshlrev_b32_e32 v174, 16, v114
	v_and_b32_e32 v175, 0xffff0000, v114
	s_waitcnt lgkmcnt(1)
	v_pk_fma_f32 v[158:159], v[76:77], v[172:173], v[158:159]
	v_add_f32_e32 v94, 1.0, v94
	s_waitcnt lgkmcnt(0)
	v_pk_fma_f32 v[158:159], v[80:81], v[174:175], v[158:159]
	v_add_f32_e32 v95, 1.0, v95
	v_mul_f32_e32 v96, 0xbfb8aa3b, v158
	v_rcp_f32_e32 v94, v94
	v_rcp_f32_e32 v95, v95
	v_exp_f32_e32 v96, v96
	v_mul_f32_e32 v171, 0xbfb8aa3b, v159
	v_pk_fma_f32 v[162:163], v[64:65], v[162:163], v[68:69]
	v_exp_f32_e32 v171, v171
	v_pk_fma_f32 v[162:163], v[72:73], v[172:173], v[162:163]
	v_lshlrev_b32_e32 v176, 16, v118
	v_and_b32_e32 v177, 0xffff0000, v118
	v_pk_fma_f32 v[162:163], v[76:77], v[174:175], v[162:163]
	v_pk_mul_f32 v[90:91], v[90:91], v[94:95]
	v_pk_fma_f32 v[162:163], v[80:81], v[176:177], v[162:163]
	v_add_f32_e32 v94, 1.0, v96
	v_mul_f32_e32 v96, 0xbfb8aa3b, v162
	v_add_f32_e32 v95, 1.0, v171
	v_exp_f32_e32 v96, v96
	v_mul_f32_e32 v171, 0xbfb8aa3b, v163
	v_rcp_f32_e32 v94, v94
	v_rcp_f32_e32 v95, v95
	v_exp_f32_e32 v171, v171
	v_pk_fma_f32 v[172:173], v[64:65], v[172:173], v[68:69]
	v_add_f32_e32 v96, 1.0, v96
	v_pk_fma_f32 v[172:173], v[72:73], v[174:175], v[172:173]
	v_lshlrev_b32_e32 v178, 16, v122
	v_and_b32_e32 v179, 0xffff0000, v122
	v_pk_fma_f32 v[172:173], v[76:77], v[176:177], v[172:173]
	v_pk_mul_f32 v[94:95], v[158:159], v[94:95]
	v_rcp_f32_e32 v158, v96
	v_add_f32_e32 v96, 1.0, v171
	v_pk_fma_f32 v[172:173], v[80:81], v[178:179], v[172:173]
	v_rcp_f32_e32 v159, v96
	v_mul_f32_e32 v96, 0xbfb8aa3b, v172
	v_exp_f32_e32 v96, v96
	v_mul_f32_e32 v171, 0xbfb8aa3b, v173
	v_exp_f32_e32 v171, v171
	v_pk_fma_f32 v[64:65], v[64:65], v[174:175], v[68:69]
	v_add_f32_e32 v96, 1.0, v96
	v_pk_fma_f32 v[64:65], v[72:73], v[176:177], v[64:65]
	v_lshlrev_b32_e32 v180, 16, v126
	v_and_b32_e32 v181, 0xffff0000, v126
	v_pk_fma_f32 v[64:65], v[76:77], v[178:179], v[64:65]
	v_pk_mul_f32 v[158:159], v[162:163], v[158:159]
	v_rcp_f32_e32 v162, v96
	v_add_f32_e32 v96, 1.0, v171
	v_pk_fma_f32 v[64:65], v[80:81], v[180:181], v[64:65]
	v_rcp_f32_e32 v163, v96
	v_mul_f32_e32 v68, 0xbfb8aa3b, v64
	v_mul_f32_e32 v69, 0xbfb8aa3b, v65
	v_exp_f32_e32 v68, v68
	v_exp_f32_e32 v69, v69
	v_lshlrev_b32_e32 v72, 16, v107
	v_and_b32_e32 v73, 0xffff0000, v107
	v_lshlrev_b32_e32 v80, 16, v103
	v_and_b32_e32 v81, 0xffff0000, v103
	v_pk_fma_f32 v[72:73], v[66:67], v[72:73], v[70:71]
	v_pk_mul_f32 v[76:77], v[172:173], v[162:163]
	v_lshlrev_b32_e32 v162, 16, v111
	v_and_b32_e32 v163, 0xffff0000, v111
	v_pk_fma_f32 v[72:73], v[74:75], v[80:81], v[72:73]
	v_add_f32_e32 v68, 1.0, v68
	v_add_f32_e32 v69, 1.0, v69
	v_lshlrev_b32_e32 v172, 16, v115
	v_and_b32_e32 v173, 0xffff0000, v115
	v_pk_fma_f32 v[72:73], v[78:79], v[162:163], v[72:73]
	v_rcp_f32_e32 v68, v68
	v_rcp_f32_e32 v69, v69
	v_pk_fma_f32 v[174:175], v[82:83], v[172:173], v[72:73]
	v_pk_fma_f32 v[80:81], v[66:67], v[80:81], v[70:71]
	v_mul_f32_e32 v72, 0xbfb8aa3b, v174
	v_exp_f32_e32 v96, v72
	v_mul_f32_e32 v72, 0xbfb8aa3b, v175
	v_exp_f32_e32 v171, v72
	v_pk_fma_f32 v[80:81], v[74:75], v[162:163], v[80:81]
	v_pk_mul_f32 v[72:73], v[64:65], v[68:69]
	v_lshlrev_b32_e32 v68, 16, v119
	v_and_b32_e32 v69, 0xffff0000, v119
	v_pk_fma_f32 v[80:81], v[78:79], v[172:173], v[80:81]
	v_add_f32_e32 v64, 1.0, v96
	v_pk_fma_f32 v[80:81], v[82:83], v[68:69], v[80:81]
	v_add_f32_e32 v65, 1.0, v171
	v_mul_f32_e32 v96, 0xbfb8aa3b, v80
	v_exp_f32_e32 v96, v96
	v_mul_f32_e32 v171, 0xbfb8aa3b, v81
	v_pk_fma_f32 v[162:163], v[66:67], v[162:163], v[70:71]
	v_pk_fma_f32 v[66:67], v[66:67], v[172:173], v[70:71]
	v_exp_f32_e32 v171, v171
	v_lshlrev_b32_e32 v178, 16, v123
	v_and_b32_e32 v179, 0xffff0000, v123
	v_pk_fma_f32 v[66:67], v[74:75], v[68:69], v[66:67]
	v_pk_fma_f32 v[162:163], v[74:75], v[172:173], v[162:163]
	v_lshlrev_b32_e32 v182, 16, v127
	v_and_b32_e32 v183, 0xffff0000, v127
	v_pk_fma_f32 v[66:67], v[78:79], v[178:179], v[66:67]
	v_pk_fma_f32 v[162:163], v[78:79], v[68:69], v[162:163]
	v_pk_fma_f32 v[74:75], v[82:83], v[182:183], v[66:67]
	v_add_f32_e32 v96, 1.0, v96
	v_pk_fma_f32 v[162:163], v[82:83], v[178:179], v[162:163]
	v_mul_f32_e32 v66, 0xbfb8aa3b, v74
	v_rcp_f32_e32 v176, v96
	v_add_f32_e32 v96, 1.0, v171
	v_mul_f32_e32 v171, 0xbfb8aa3b, v162
	v_exp_f32_e32 v66, v66
	v_mul_f32_e32 v67, 0xbfb8aa3b, v75
	v_exp_f32_e32 v171, v171
	v_mul_f32_e32 v177, 0xbfb8aa3b, v163
	v_exp_f32_e32 v67, v67
	v_exp_f32_e32 v181, v177
	v_add_f32_e32 v66, 1.0, v66
	v_rcp_f32_e32 v177, v96
	v_add_f32_e32 v96, 1.0, v171
	v_rcp_f32_e32 v78, v66
	v_add_f32_e32 v66, 1.0, v67
	v_rcp_f32_e32 v64, v64
	v_rcp_f32_e32 v65, v65
	v_rcp_f32_e32 v180, v96
	v_add_f32_e32 v96, 1.0, v181
	v_rcp_f32_e32 v79, v66
	v_rcp_f32_e32 v181, v96
	v_pk_mul_f32 v[70:71], v[174:175], v[64:65]
	v_pk_mul_f32 v[68:69], v[80:81], v[176:177]
	v_pk_mul_f32 v[64:65], v[74:75], v[78:79]
	v_lshlrev_b32_e32 v74, 4, v215
	v_mul_lo_u32 v75, v170, s12
	v_pk_mul_f32 v[66:67], v[162:163], v[180:181]
	v_add3_u32 v96, 0, v74, v75
	s_and_saveexec_b64 s[12:13], vcc
	s_xor_b64 s[12:13], exec, s[12:13]
	s_cbranch_execz .LBB0_213
	v_cvt_pk_bf16_f32 v78, v92, v93
	v_cvt_pk_bf16_f32 v79, v160, v161
	v_cvt_pk_bf16_f32 v80, v94, v95
	v_cvt_pk_bf16_f32 v81, v70, v71
	ds_write_b128 v96, v[78:81]
	v_cvt_pk_bf16_f32 v81, v68, v69
	v_cvt_pk_bf16_f32 v68, v84, v85
	v_cvt_pk_bf16_f32 v69, v86, v87
	v_cvt_pk_bf16_f32 v70, v76, v77
	v_cvt_pk_bf16_f32 v71, v66, v67
	v_cvt_pk_bf16_f32 v78, v88, v89
	v_cvt_pk_bf16_f32 v79, v166, v167
	v_cvt_pk_bf16_f32 v80, v158, v159
	ds_write_b128 v96, v[68:71] offset:544
	v_cvt_pk_bf16_f32 v66, v156, v157
	v_cvt_pk_bf16_f32 v67, v90, v91
	v_cvt_pk_bf16_f32 v68, v72, v73
	v_cvt_pk_bf16_f32 v69, v64, v65
	ds_write_b128 v96, v[78:81] offset:272
	ds_write_b128 v96, v[66:69] offset:816

.Lmls_2:
	s_add_u32 s12, s74, s4
	s_addc_u32 s13, s75, s31
	s_waitcnt lgkmcnt(0)
	v_lshl_add_u64 v[64:65], s[12:13], 0, v[96:97]
	v_add_co_u32_e32 v66, vcc, 0xf000000, v64
	s_waitcnt lgkmcnt(0)
	s_barrier
	v_lshrrev_b32_e32 v218, 5, v168
	s_nop 0
	v_addc_co_u32_e32 v67, vcc, 0, v65, vcc
	v_mov_b64_e32 v[206:207], v[66:67]
	v_mov_b64_e32 v[204:205], v[66:67]
	v_add_co_u32_e32 v66, vcc, 0xf001000, v64
	v_lshlrev_b32_e32 v217, 4, v218
	s_nop 0
	v_addc_co_u32_e32 v67, vcc, 0, v65, vcc
	v_mov_b64_e32 v[202:203], v[66:67]
	v_mov_b64_e32 v[200:201], v[66:67]
	v_add_co_u32_e32 v66, vcc, 0xf002000, v64
	v_add_u32_e32 v208, 0, v217
	s_nop 0
	v_addc_co_u32_e32 v67, vcc, 0, v65, vcc
	v_add_co_u32_e32 v64, vcc, 0xf003000, v64
	v_mov_b64_e32 v[198:199], v[66:67]
	v_mov_b64_e32 v[196:197], v[66:67]
	v_addc_co_u32_e32 v65, vcc, 0, v65, vcc
	v_mov_b64_e32 v[194:195], v[64:65]
	v_mov_b64_e32 v[192:193], v[64:65]
	v_lshlrev_b32_e32 v64, 4, v168
	s_nop 0
	v_mov_b32_e32 v64, s10
	ds_read_b32 v96, v64
	v_or_b32_e32 v64, s11, v215
	v_lshlrev_b32_e32 v68, 3, v218
	v_mul_u32_u24_e32 v69, 0x110, v215
	v_mad_u64_u32 v[64:65], s[12:13], v64, s93, v[208:209]
	v_add3_u32 v176, 0, v68, v69
	ds_read_b128 v[168:171], v64 offset:53248
	ds_read_b128 v[164:167], v64 offset:53280
	ds_read_b128 v[160:163], v64 offset:53312
	ds_read_b128 v[156:159], v64 offset:53344
	v_add_u32_e32 v177, 0x2000, v176
	s_add_i32 s12, 0, 0x20b00
	v_add_u32_e32 v220, s12, v217
	v_add_u32_e32 v219, s15, v217
	s_add_i32 s13, 0, 0x20d00
	s_add_i32 s15, 0, 0x20e00
	s_add_i32 s42, 0, 0x20f00
	s_movk_i32 s43, 0x840
	v_or_b32_e32 v216, 32, v215
	ds_read2_b64 v[232:235], v176 offset0:0 offset1:2
	ds_read2_b64 v[236:239], v177 offset0:64 offset1:66
	ds_read2_b64 v[240:243], v176 offset0:4 offset1:6
	ds_read2_b64 v[180:183], v177 offset0:68 offset1:70
	v_cvt_pk_bf16_f32 v172, v0, v1
	v_cvt_pk_bf16_f32 v173, v2, v3
	v_cvt_pk_bf16_f32 v174, v4, v5
	v_cvt_pk_bf16_f32 v175, v6, v7
	s_nop 0
	s_waitcnt lgkmcnt(3)
	v_mfma_f32_32x32x16_bf16 v[80:95], v[232:235], v[172:175], 0
	ds_read2_b64 v[232:235], v176 offset0:8 offset1:10
	s_waitcnt lgkmcnt(3)
	v_mfma_f32_32x32x16_bf16 v[64:79], v[236:239], v[172:175], 0
	ds_read2_b64 v[236:239], v177 offset0:72 offset1:74
	v_cvt_pk_bf16_f32 v244, v8, v9
	v_cvt_pk_bf16_f32 v245, v10, v11
	v_cvt_pk_bf16_f32 v246, v12, v13
	v_cvt_pk_bf16_f32 v247, v14, v15
	v_pk_mul_f32 v[0:1], v[0:1], v[96:97] op_sel_hi:[1,0]
	v_pk_mul_f32 v[2:3], v[2:3], v[96:97] op_sel_hi:[1,0]
	v_pk_mul_f32 v[4:5], v[4:5], v[96:97] op_sel_hi:[1,0]
	v_pk_mul_f32 v[6:7], v[6:7], v[96:97] op_sel_hi:[1,0]
	s_waitcnt lgkmcnt(3)
	v_mfma_f32_32x32x16_bf16 v[80:95], v[240:243], v[244:247], v[80:95]
	ds_read2_b64 v[240:243], v176 offset0:12 offset1:14
	s_waitcnt lgkmcnt(3)
	v_mfma_f32_32x32x16_bf16 v[64:79], v[180:183], v[244:247], v[64:79]
	ds_read2_b64 v[180:183], v177 offset0:76 offset1:78
	global_load_dwordx2 v[206:207], v[206:207], off sc1
	v_cvt_pk_bf16_f32 v172, v16, v17
	v_cvt_pk_bf16_f32 v173, v18, v19
	v_cvt_pk_bf16_f32 v174, v20, v21
	v_cvt_pk_bf16_f32 v175, v22, v23
	v_pk_mul_f32 v[8:9], v[8:9], v[96:97] op_sel_hi:[1,0]
	v_pk_mul_f32 v[10:11], v[10:11], v[96:97] op_sel_hi:[1,0]
	v_pk_mul_f32 v[12:13], v[12:13], v[96:97] op_sel_hi:[1,0]
	v_pk_mul_f32 v[14:15], v[14:15], v[96:97] op_sel_hi:[1,0]
	s_waitcnt lgkmcnt(3)
	v_mfma_f32_32x32x16_bf16 v[80:95], v[232:235], v[172:175], v[80:95]
	ds_read2_b64 v[232:235], v176 offset0:16 offset1:18
	s_waitcnt lgkmcnt(3)
	v_mfma_f32_32x32x16_bf16 v[64:79], v[236:239], v[172:175], v[64:79]
	ds_read2_b64 v[236:239], v177 offset0:80 offset1:82
	v_cvt_pk_bf16_f32 v244, v24, v25
	v_cvt_pk_bf16_f32 v245, v26, v27
	v_cvt_pk_bf16_f32 v246, v28, v29
	v_cvt_pk_bf16_f32 v247, v30, v31
	v_pk_mul_f32 v[16:17], v[16:17], v[96:97] op_sel_hi:[1,0]
	v_pk_mul_f32 v[18:19], v[18:19], v[96:97] op_sel_hi:[1,0]
	v_pk_mul_f32 v[20:21], v[20:21], v[96:97] op_sel_hi:[1,0]
	v_pk_mul_f32 v[22:23], v[22:23], v[96:97] op_sel_hi:[1,0]
	s_waitcnt lgkmcnt(3)
	v_mfma_f32_32x32x16_bf16 v[80:95], v[240:243], v[244:247], v[80:95]
	ds_read2_b64 v[240:243], v176 offset0:20 offset1:22
	s_waitcnt lgkmcnt(3)
	v_mfma_f32_32x32x16_bf16 v[64:79], v[180:183], v[244:247], v[64:79]
	ds_read2_b64 v[180:183], v177 offset0:84 offset1:86
	global_load_dwordx2 v[204:205], v[204:205], off offset:2048 sc1
	v_cvt_pk_bf16_f32 v172, v32, v33
	v_cvt_pk_bf16_f32 v173, v34, v35
	v_cvt_pk_bf16_f32 v174, v36, v37
	v_cvt_pk_bf16_f32 v175, v38, v39
	v_pk_mul_f32 v[24:25], v[24:25], v[96:97] op_sel_hi:[1,0]
	v_pk_mul_f32 v[26:27], v[26:27], v[96:97] op_sel_hi:[1,0]
	v_pk_mul_f32 v[28:29], v[28:29], v[96:97] op_sel_hi:[1,0]
	v_pk_mul_f32 v[30:31], v[30:31], v[96:97] op_sel_hi:[1,0]
	s_waitcnt lgkmcnt(3)
	v_mfma_f32_32x32x16_bf16 v[80:95], v[232:235], v[172:175], v[80:95]
	ds_read2_b64 v[232:235], v176 offset0:24 offset1:26
	s_waitcnt lgkmcnt(3)
	v_mfma_f32_32x32x16_bf16 v[64:79], v[236:239], v[172:175], v[64:79]
	ds_read2_b64 v[236:239], v177 offset0:88 offset1:90
	v_cvt_pk_bf16_f32 v244, v40, v41
	v_cvt_pk_bf16_f32 v245, v42, v43
	v_cvt_pk_bf16_f32 v246, v44, v45
	v_cvt_pk_bf16_f32 v247, v46, v47
	v_pk_mul_f32 v[32:33], v[32:33], v[96:97] op_sel_hi:[1,0]
	v_pk_mul_f32 v[34:35], v[34:35], v[96:97] op_sel_hi:[1,0]
	v_pk_mul_f32 v[36:37], v[36:37], v[96:97] op_sel_hi:[1,0]
	v_pk_mul_f32 v[38:39], v[38:39], v[96:97] op_sel_hi:[1,0]
	s_waitcnt lgkmcnt(3)
	v_mfma_f32_32x32x16_bf16 v[80:95], v[240:243], v[244:247], v[80:95]
	ds_read2_b64 v[240:243], v176 offset0:28 offset1:30
	s_waitcnt lgkmcnt(3)
	v_mfma_f32_32x32x16_bf16 v[64:79], v[180:183], v[244:247], v[64:79]
	ds_read2_b64 v[180:183], v177 offset0:92 offset1:94
	global_load_dwordx2 v[202:203], v[202:203], off sc1
	v_cvt_pk_bf16_f32 v172, v48, v49
	v_cvt_pk_bf16_f32 v173, v50, v51
	v_cvt_pk_bf16_f32 v174, v52, v53
	v_cvt_pk_bf16_f32 v175, v54, v55
	v_pk_mul_f32 v[40:41], v[40:41], v[96:97] op_sel_hi:[1,0]
	v_pk_mul_f32 v[42:43], v[42:43], v[96:97] op_sel_hi:[1,0]
	v_pk_mul_f32 v[44:45], v[44:45], v[96:97] op_sel_hi:[1,0]
	v_pk_mul_f32 v[46:47], v[46:47], v[96:97] op_sel_hi:[1,0]
	s_waitcnt lgkmcnt(3)
	v_mfma_f32_32x32x16_bf16 v[80:95], v[232:235], v[172:175], v[80:95]
	s_waitcnt lgkmcnt(2)
	v_mfma_f32_32x32x16_bf16 v[64:79], v[236:239], v[172:175], v[64:79]
	v_cvt_pk_bf16_f32 v244, v56, v57
	v_cvt_pk_bf16_f32 v245, v58, v59
	v_cvt_pk_bf16_f32 v246, v60, v61
	v_cvt_pk_bf16_f32 v247, v62, v63
	v_pk_mul_f32 v[48:49], v[48:49], v[96:97] op_sel_hi:[1,0]
	v_pk_mul_f32 v[50:51], v[50:51], v[96:97] op_sel_hi:[1,0]
	v_pk_mul_f32 v[52:53], v[52:53], v[96:97] op_sel_hi:[1,0]
	v_pk_mul_f32 v[54:55], v[54:55], v[96:97] op_sel_hi:[1,0]
	s_waitcnt lgkmcnt(1)
	v_mfma_f32_32x32x16_bf16 v[80:95], v[240:243], v[244:247], v[80:95]
	v_pk_mul_f32 v[56:57], v[56:57], v[96:97] op_sel_hi:[1,0]
	v_pk_mul_f32 v[58:59], v[58:59], v[96:97] op_sel_hi:[1,0]
	v_pk_mul_f32 v[60:61], v[60:61], v[96:97] op_sel_hi:[1,0]
	v_pk_mul_f32 v[62:63], v[62:63], v[96:97] op_sel_hi:[1,0]
	v_lshl_add_u32 v176, v215, 1, s2
	v_mad_u32_u24 v177, v215, s93, v219
	s_waitcnt lgkmcnt(0)
	v_mfma_f32_32x32x16_bf16 v[64:79], v[180:183], v[244:247], v[64:79]
	global_load_dwordx2 v[200:201], v[200:201], off offset:2048 sc1
	ds_read_b128 v[172:175], v220
	ds_read_b128 v[232:235], v220 offset:32
	ds_read_b128 v[236:239], v220 offset:64
	ds_read_b128 v[240:243], v220 offset:96
	s_waitcnt lgkmcnt(3)
	v_pk_mul_f32 v[82:83], v[82:83], v[174:175]
	s_waitcnt lgkmcnt(2)
	v_pk_mul_f32 v[86:87], v[86:87], v[234:235]
	s_waitcnt lgkmcnt(1)
	v_pk_mul_f32 v[90:91], v[90:91], v[238:239]
	v_pk_mul_f32 v[88:89], v[88:89], v[236:237]
	v_pk_mul_f32 v[84:85], v[84:85], v[232:233]
	ds_read_b128 v[232:235], v177
	ds_read_b128 v[236:239], v177 offset:32
	s_waitcnt lgkmcnt(2)
	v_pk_mul_f32 v[94:95], v[94:95], v[242:243]
	v_pk_mul_f32 v[92:93], v[92:93], v[240:241]
	v_pk_mul_f32 v[80:81], v[80:81], v[172:173]
	s_waitcnt lgkmcnt(1)
	s_nop 0
	v_mfma_f32_32x32x16_bf16 v[80:95], v[232:235], v[168:171], v[80:95]
	ds_read_b128 v[232:235], v177 offset:64
	s_waitcnt lgkmcnt(1)
	v_mfma_f32_32x32x16_bf16 v[80:95], v[236:239], v[164:167], v[80:95]
	s_waitcnt lgkmcnt(0)
	v_mfma_f32_32x32x16_bf16 v[80:95], v[232:235], v[160:163], v[80:95]
	ds_read_b128 v[232:235], v177 offset:96
	v_add_u32_e32 v177, s13, v217
	s_waitcnt lgkmcnt(0)
	v_mfma_f32_32x32x16_bf16 v[80:95], v[232:235], v[156:159], v[80:95]
	s_cmpk_eq_i32 s82, 0x7c0
	s_cbranch_scc1 .Lmls_3
	buffer_load_dwordx4 v[128:131], v128, s[76:79], 0 offen sc1
.Lmls_3:
	ds_read_b128 v[232:235], v177
	v_add_u32_e32 v177, s15, v217
	ds_read_b128 v[236:239], v177
	v_add_u32_e32 v177, s42, v217
	ds_read_b128 v[240:243], v177
	s_waitcnt lgkmcnt(1)
	v_fma_f32 v172, v172, v232, v236
	v_fmac_f32_e32 v239, v175, v235
	s_waitcnt lgkmcnt(0)
	v_max_f32_e32 v177, v240, v240
	v_max_f32_e64 v172, |v172|, v177
	v_rcp_f32_e32 v172, v172
	s_nop 0
	v_mul_f32_e32 v80, v80, v172
	v_cvt_pk_bf16_f32 v172, v80, s0
	v_mad_u32_u24 v80, v218, s43, v176
	ds_write_b16 v80, v172
	v_fma_f32 v172, v173, v233, v237
	v_max_f32_e32 v173, v241, v241
	v_max_f32_e64 v172, |v172|, v173
	v_rcp_f32_e32 v172, v172
	s_nop 0
	v_mul_f32_e32 v81, v81, v172
	v_cvt_pk_bf16_f32 v81, v81, s0
	ds_write_b16 v80, v81 offset:528
	v_fma_f32 v81, v174, v234, v238
	v_max_f32_e32 v172, v242, v242
	v_max_f32_e64 v81, |v81|, v172
	v_rcp_f32_e32 v81, v81
	s_nop 0
	v_mul_f32_e32 v81, v82, v81
	v_cvt_pk_bf16_f32 v81, v81, s0
	ds_write_b16 v80, v81 offset:1056
	v_max_f32_e32 v81, v243, v243
	v_max_f32_e64 v81, |v239|, v81
	v_rcp_f32_e32 v81, v81
	s_nop 0
	v_mul_f32_e32 v81, v83, v81
	v_cvt_pk_bf16_f32 v81, v81, s0
	ds_write_b16 v80, v81 offset:1584
	global_load_dwordx2 v[198:199], v[198:199], off sc1
	v_lshl_or_b32 v81, v218, 2, 8
	v_lshlrev_b32_e32 v82, 2, v81
	v_add_u32_e32 v83, s12, v82
	ds_read_b128 v[172:175], v83
	v_add_u32_e32 v83, s13, v82
	ds_read_b128 v[232:235], v83
	v_add_u32_e32 v83, s15, v82
	v_add_u32_e32 v82, s42, v82
	ds_read_b128 v[236:239], v83
	ds_read_b128 v[240:243], v82
	v_mad_u32_u24 v81, v81, s85, v176
	s_waitcnt lgkmcnt(1)
	v_fma_f32 v82, v172, v232, v236
	s_waitcnt lgkmcnt(0)
	v_max_f32_e32 v83, v240, v240
	v_max_f32_e64 v82, |v82|, v83
	v_rcp_f32_e32 v82, v82
	v_max_f32_e32 v83, v241, v241
	v_fmac_f32_e32 v239, v175, v235
	v_mul_f32_e32 v82, v84, v82
	v_cvt_pk_bf16_f32 v82, v82, s0
	ds_write_b16 v81, v82
	v_fma_f32 v82, v173, v233, v237
	v_max_f32_e64 v82, |v82|, v83
	v_rcp_f32_e32 v82, v82
	v_max_f32_e32 v83, v242, v242
	v_mul_f32_e32 v82, v85, v82
	v_cvt_pk_bf16_f32 v82, v82, s0
	ds_write_b16 v80, v82 offset:4752
	v_fma_f32 v82, v174, v234, v238
	v_max_f32_e64 v82, |v82|, v83
	v_rcp_f32_e32 v82, v82
	s_nop 0
	v_mul_f32_e32 v82, v86, v82
	v_cvt_pk_bf16_f32 v82, v82, s0
	ds_write_b16 v80, v82 offset:5280
	v_max_f32_e32 v82, v243, v243
	v_max_f32_e64 v82, |v239|, v82
	v_rcp_f32_e32 v82, v82
	v_or_b32_e32 v86, 64, v217
	v_mul_f32_e32 v82, v87, v82
	v_cvt_pk_bf16_f32 v82, v82, s0
	ds_write_b16 v80, v82 offset:5808
	s_cmpk_eq_i32 s82, 0x7c0
	s_cbranch_scc1 .Lmls_4
	buffer_load_dwordx4 v[140:143], v140, s[76:79], 0 offen sc1
.Lmls_4:
	v_add_u32_e32 v87, s13, v86
	v_add_u32_e32 v82, s12, v86
	ds_read_b128 v[172:175], v87
	v_add_u32_e32 v87, s15, v86
	v_add_u32_e32 v86, s42, v86
	ds_read_b128 v[82:85], v82
	ds_read_b128 v[236:239], v86
	ds_read_b128 v[232:235], v87
	s_waitcnt lgkmcnt(1)
	v_max_f32_e32 v86, v236, v236
	s_waitcnt lgkmcnt(0)
	v_fma_f32 v82, v82, v172, v232
	v_max_f32_e64 v82, |v82|, v86
	v_rcp_f32_e32 v82, v82
	v_fmac_f32_e32 v235, v85, v175
	v_mul_f32_e32 v82, v88, v82
	v_cvt_pk_bf16_f32 v82, v82, s0
	ds_write_b16 v81, v82 offset:4224
	v_fma_f32 v82, v83, v173, v233
	v_max_f32_e32 v83, v237, v237
	v_max_f32_e64 v82, |v82|, v83
	v_rcp_f32_e32 v82, v82
	v_max_f32_e32 v83, v238, v238
	v_mul_f32_e32 v82, v89, v82
	v_cvt_pk_bf16_f32 v82, v82, s0
	ds_write_b16 v80, v82 offset:8976
	v_fma_f32 v82, v84, v174, v234
	v_max_f32_e64 v82, |v82|, v83
	v_rcp_f32_e32 v82, v82
	s_nop 0
	v_mul_f32_e32 v82, v90, v82
	v_cvt_pk_bf16_f32 v82, v82, s0
	ds_write_b16 v80, v82 offset:9504
	v_max_f32_e32 v82, v239, v239
	v_max_f32_e64 v82, |v235|, v82
	v_rcp_f32_e32 v82, v82
	v_or_b32_e32 v90, 0x60, v217
	v_add_u32_e32 v86, s13, v90
	v_mul_f32_e32 v82, v91, v82
	v_cvt_pk_bf16_f32 v82, v82, s0
	ds_write_b16 v80, v82 offset:10032
	global_load_dwordx2 v[196:197], v[196:197], off offset:2048 sc1
	v_add_u32_e32 v82, s12, v90
	v_add_u32_e32 v91, s15, v90
	v_add_u32_e32 v90, s42, v90
	ds_read_b128 v[82:85], v82
	ds_read_b128 v[86:89], v86
	ds_read_b128 v[172:175], v91
	ds_read_b128 v[232:235], v90
	s_waitcnt lgkmcnt(1)
	v_fma_f32 v82, v82, v86, v172
	s_waitcnt lgkmcnt(0)
	v_max_f32_e32 v86, v232, v232
	v_max_f32_e64 v82, |v82|, v86
	v_rcp_f32_e32 v82, v82
	v_fmac_f32_e32 v175, v85, v89
	v_mul_f32_e32 v82, v92, v82
	v_cvt_pk_bf16_f32 v82, v82, s0
	ds_write_b16 v81, v82 offset:8448
	v_fma_f32 v82, v83, v87, v173
	v_max_f32_e32 v83, v233, v233
	v_max_f32_e64 v82, |v82|, v83
	v_rcp_f32_e32 v82, v82
	v_max_f32_e32 v83, v234, v234
	v_mul_f32_e32 v82, v93, v82
	v_cvt_pk_bf16_f32 v82, v82, s0
	ds_write_b16 v80, v82 offset:13200
	v_fma_f32 v82, v84, v88, v174
	v_max_f32_e64 v82, |v82|, v83
	v_rcp_f32_e32 v82, v82
	s_nop 0
	v_mul_f32_e32 v82, v94, v82
	v_cvt_pk_bf16_f32 v82, v82, s0
	ds_write_b16 v80, v82 offset:13728
	v_max_f32_e32 v82, v235, v235
	v_max_f32_e64 v82, |v175|, v82
	v_rcp_f32_e32 v82, v82
	v_mad_u32_u24 v94, v216, s93, v219
	v_mul_f32_e32 v82, v95, v82
	v_cvt_pk_bf16_f32 v82, v82, s0
	ds_write_b16 v80, v82 offset:14256
	s_cmpk_eq_i32 s82, 0x7c0
	s_cbranch_scc1 .Lmls_5
	buffer_load_dwordx4 v[144:147], v144, s[76:79], 0 offen sc1
.Lmls_5:
	ds_read_b128 v[82:85], v220 offset:128
	ds_read_b128 v[86:89], v220 offset:160
	ds_read_b128 v[90:93], v220 offset:192
	ds_read_b128 v[172:175], v220 offset:224
	s_waitcnt lgkmcnt(3)
	v_pk_mul_f32 v[66:67], v[66:67], v[84:85]
	s_waitcnt lgkmcnt(2)
	v_pk_mul_f32 v[68:69], v[68:69], v[86:87]
	s_waitcnt lgkmcnt(1)
	v_pk_mul_f32 v[72:73], v[72:73], v[90:91]
	v_pk_mul_f32 v[74:75], v[74:75], v[92:93]
	v_pk_mul_f32 v[70:71], v[70:71], v[88:89]
	ds_read_b128 v[86:89], v94
	ds_read_b128 v[90:93], v94 offset:32
	s_waitcnt lgkmcnt(2)
	v_pk_mul_f32 v[76:77], v[76:77], v[172:173]
	v_pk_mul_f32 v[78:79], v[78:79], v[174:175]
	v_pk_mul_f32 v[64:65], v[64:65], v[82:83]
	s_waitcnt lgkmcnt(1)
	s_nop 0
	v_mfma_f32_32x32x16_bf16 v[64:79], v[86:89], v[168:171], v[64:79]
	ds_read_b128 v[86:89], v94 offset:64
	s_waitcnt lgkmcnt(1)
	v_mfma_f32_32x32x16_bf16 v[64:79], v[90:93], v[164:167], v[64:79]
	s_waitcnt lgkmcnt(0)
	v_mfma_f32_32x32x16_bf16 v[64:79], v[86:89], v[160:163], v[64:79]
	ds_read_b128 v[86:89], v94 offset:96
	v_or_b32_e32 v94, 0x80, v217
	v_add_u32_e32 v90, s15, v94
	ds_read_b128 v[90:93], v90
	s_waitcnt lgkmcnt(1)
	v_mfma_f32_32x32x16_bf16 v[64:79], v[86:89], v[156:159], v[64:79]
	global_load_dwordx2 v[194:195], v[194:195], off sc1
	v_add_u32_e32 v86, s13, v94
	v_add_u32_e32 v94, s42, v94
	ds_read_b128 v[86:89], v86
	ds_read_b128 v[172:175], v94
	s_waitcnt lgkmcnt(1)
	v_fma_f32 v82, v82, v86, v90
	s_waitcnt lgkmcnt(0)
	v_max_f32_e32 v86, v172, v172
	v_max_f32_e64 v82, |v82|, v86
	v_rcp_f32_e32 v82, v82
	v_fmac_f32_e32 v93, v85, v89
	v_or_b32_e32 v90, 0xa0, v217
	v_add_u32_e32 v86, s15, v90
	v_mul_f32_e32 v64, v64, v82
	v_cvt_pk_bf16_f32 v64, v64, s0
	ds_write_b16 v81, v64 offset:12672
	v_fma_f32 v64, v83, v87, v91
	v_max_f32_e32 v82, v173, v173
	v_max_f32_e64 v64, |v64|, v82
	v_rcp_f32_e32 v64, v64
	v_add_u32_e32 v82, s13, v90
	v_mul_f32_e32 v64, v65, v64
	v_cvt_pk_bf16_f32 v64, v64, s0
	ds_write_b16 v80, v64 offset:17424
	v_fma_f32 v64, v84, v88, v92
	v_max_f32_e32 v65, v174, v174
	v_max_f32_e64 v64, |v64|, v65
	v_rcp_f32_e32 v64, v64
	s_nop 0
	v_mul_f32_e32 v64, v66, v64
	v_cvt_pk_bf16_f32 v64, v64, s0
	ds_write_b16 v80, v64 offset:17952
	v_max_f32_e32 v64, v175, v175
	v_max_f32_e64 v64, |v93|, v64
	v_rcp_f32_e32 v64, v64
	s_nop 0
	v_mul_f32_e32 v64, v67, v64
	v_cvt_pk_bf16_f32 v64, v64, s0
	ds_write_b16 v80, v64 offset:18480
	s_cmpk_eq_i32 s82, 0x7c0
	s_cbranch_scc1 .Lmls_6
	buffer_load_dwordx4 v[148:151], v148, s[76:79], 0 offen sc1
.Lmls_6:
	v_add_u32_e32 v64, s12, v90
	v_add_u32_e32 v90, s42, v90
	ds_read_b128 v[64:67], v64
	ds_read_b128 v[82:85], v82
	ds_read_b128 v[86:89], v86
	ds_read_b128 v[90:93], v90
	s_waitcnt lgkmcnt(1)
	v_fma_f32 v64, v64, v82, v86
	s_waitcnt lgkmcnt(0)
	v_max_f32_e32 v82, v90, v90
	v_max_f32_e64 v64, |v64|, v82
	v_rcp_f32_e32 v64, v64
	v_fmac_f32_e32 v89, v67, v85
	v_or_b32_e32 v86, 0xc0, v217
	v_add_u32_e32 v82, s15, v86
	v_mul_f32_e32 v64, v68, v64
	v_cvt_pk_bf16_f32 v64, v64, s0
	ds_write_b16 v81, v64 offset:16896
	v_fma_f32 v64, v65, v83, v87
	v_max_f32_e32 v65, v91, v91
	v_max_f32_e64 v64, |v64|, v65
	v_rcp_f32_e32 v64, v64
	v_max_f32_e32 v65, v92, v92
	v_add_u32_e32 v68, s13, v86
	v_mul_f32_e32 v64, v69, v64
	v_cvt_pk_bf16_f32 v64, v64, s0
	ds_write_b16 v80, v64 offset:21648
	v_fma_f32 v64, v66, v84, v88
	v_max_f32_e64 v64, |v64|, v65
	v_rcp_f32_e32 v64, v64
	s_nop 0
	v_mul_f32_e32 v64, v70, v64
	v_cvt_pk_bf16_f32 v64, v64, s0
	ds_write_b16 v80, v64 offset:22176
	v_max_f32_e32 v64, v93, v93
	v_max_f32_e64 v64, |v89|, v64
	v_rcp_f32_e32 v64, v64
	s_nop 0
	v_mul_f32_e32 v64, v71, v64
	v_cvt_pk_bf16_f32 v64, v64, s0
	ds_write_b16 v80, v64 offset:22704
	global_load_dwordx2 v[192:193], v[192:193], off offset:2048 sc1
	v_add_u32_e32 v64, s12, v86
	v_add_u32_e32 v86, s42, v86
	ds_read_b128 v[64:67], v64
	ds_read_b128 v[68:71], v68
	ds_read_b128 v[82:85], v82
	ds_read_b128 v[86:89], v86
	s_waitcnt lgkmcnt(1)
	v_fma_f32 v64, v64, v68, v82
	s_waitcnt lgkmcnt(0)
	v_max_f32_e32 v68, v86, v86
	v_max_f32_e64 v64, |v64|, v68
	v_rcp_f32_e32 v64, v64
	v_fmac_f32_e32 v85, v67, v71
	v_or_b32_e32 v82, 0xe0, v217
	v_add_u32_e32 v68, s13, v82
	v_mul_f32_e32 v64, v72, v64
	v_cvt_pk_bf16_f32 v64, v64, s0
	ds_write_b16 v81, v64 offset:21120
	v_fma_f32 v64, v65, v69, v83
	v_max_f32_e32 v65, v87, v87
	v_max_f32_e64 v64, |v64|, v65
	v_rcp_f32_e32 v64, v64
	v_max_f32_e32 v65, v88, v88
	v_add_u32_e32 v72, s15, v82
	v_mul_f32_e32 v64, v73, v64
	v_cvt_pk_bf16_f32 v64, v64, s0
	ds_write_b16 v80, v64 offset:25872
	v_fma_f32 v64, v66, v70, v84
	v_max_f32_e64 v64, |v64|, v65
	v_rcp_f32_e32 v64, v64
	s_nop 0
	v_mul_f32_e32 v64, v74, v64
	v_cvt_pk_bf16_f32 v64, v64, s0
	ds_write_b16 v80, v64 offset:26400
	v_max_f32_e32 v64, v89, v89
	v_max_f32_e64 v64, |v85|, v64
	v_rcp_f32_e32 v64, v64
	s_nop 0
	v_mul_f32_e32 v64, v75, v64
	v_cvt_pk_bf16_f32 v64, v64, s0
	ds_write_b16 v80, v64 offset:26928
	v_add_u32_e32 v64, s12, v82
	v_add_u32_e32 v82, s42, v82
	ds_read_b128 v[64:67], v64
	ds_read_b128 v[68:71], v68
	ds_read_b128 v[72:75], v72
	ds_read_b128 v[82:85], v82
	s_waitcnt lgkmcnt(1)
	v_fma_f32 v64, v64, v68, v72
	s_waitcnt lgkmcnt(0)
	v_max_f32_e32 v68, v82, v82
	v_max_f32_e64 v64, |v64|, v68
	v_rcp_f32_e32 v64, v64
	v_fmac_f32_e32 v75, v67, v71
	v_mad_u32_u24 v72, v215, s93, v208
	v_mul_f32_e32 v64, v76, v64
	v_cvt_pk_bf16_f32 v64, v64, s0
	ds_write_b16 v81, v64 offset:25344
	v_fma_f32 v64, v65, v69, v73
	v_max_f32_e32 v65, v83, v83
	v_max_f32_e64 v64, |v64|, v65
	v_rcp_f32_e32 v64, v64
	v_max_f32_e32 v65, v84, v84
	v_mad_u32_u24 v73, v216, s93, v208
	v_mul_f32_e32 v64, v77, v64
	v_cvt_pk_bf16_f32 v64, v64, s0
	ds_write_b16 v80, v64 offset:30096
	v_fma_f32 v64, v66, v70, v74
	v_max_f32_e64 v64, |v64|, v65
	v_rcp_f32_e32 v64, v64
	v_and_b32_e32 v74, 3, v214
	v_cmp_eq_u32_e32 vcc, 0, v74
	v_mul_f32_e32 v64, v78, v64
	v_cvt_pk_bf16_f32 v64, v64, s0
	ds_write_b16 v80, v64 offset:30624
	v_max_f32_e32 v64, v85, v85
	v_max_f32_e64 v64, |v75|, v64
	v_rcp_f32_e32 v64, v64
	s_nop 0
	v_mul_f32_e32 v64, v79, v64
	v_cvt_pk_bf16_f32 v64, v64, s0
	ds_write_b16 v80, v64 offset:31152
	ds_read_b128 v[64:67], v72 offset:34816
	ds_read_b128 v[68:71], v72 offset:34848
	ds_read_b128 v[76:79], v72 offset:34880
	ds_read_b128 v[80:83], v72 offset:34912
	ds_read_b128 v[84:87], v73 offset:34816
	ds_read_b128 v[88:91], v73 offset:34848
	s_waitcnt lgkmcnt(5)
	v_mfma_f32_32x32x16_bf16 v[0:15], v[64:67], v[168:171], v[0:15]
	ds_read_b128 v[64:67], v73 offset:34880
	s_waitcnt lgkmcnt(5)
	v_mfma_f32_32x32x16_bf16 v[0:15], v[68:71], v[164:167], v[0:15]
	ds_read_b128 v[68:71], v73 offset:34912
	s_waitcnt lgkmcnt(5)
	v_mfma_f32_32x32x16_bf16 v[0:15], v[76:79], v[160:163], v[0:15]
	ds_read_b128 v[76:79], v72 offset:44032
	s_waitcnt lgkmcnt(5)
	v_mfma_f32_32x32x16_bf16 v[0:15], v[80:83], v[156:159], v[0:15]
	ds_read_b128 v[80:83], v72 offset:44064
	s_waitcnt lgkmcnt(5)
	v_mfma_f32_32x32x16_bf16 v[16:31], v[84:87], v[168:171], v[16:31]
	ds_read_b128 v[84:87], v72 offset:44096
	s_waitcnt lgkmcnt(5)
	v_mfma_f32_32x32x16_bf16 v[16:31], v[88:91], v[164:167], v[16:31]
	ds_read_b128 v[88:91], v72 offset:44128
	s_waitcnt lgkmcnt(5)
	v_mfma_f32_32x32x16_bf16 v[16:31], v[64:67], v[160:163], v[16:31]
	ds_read_b128 v[64:67], v72 offset:48640
	s_waitcnt lgkmcnt(5)
	v_mfma_f32_32x32x16_bf16 v[16:31], v[68:71], v[156:159], v[16:31]
	ds_read_b128 v[68:71], v72 offset:48672
	s_waitcnt lgkmcnt(5)
	v_mfma_f32_32x32x16_bf16 v[32:47], v[76:79], v[168:171], v[32:47]
	ds_read_b128 v[76:79], v72 offset:48704
	s_waitcnt lgkmcnt(5)
	v_mfma_f32_32x32x16_bf16 v[32:47], v[80:83], v[164:167], v[32:47]
	ds_read_b128 v[80:83], v72 offset:48736
	s_waitcnt lgkmcnt(5)
	v_mfma_f32_32x32x16_bf16 v[32:47], v[84:87], v[160:163], v[32:47]
	s_waitcnt lgkmcnt(4)
	v_mfma_f32_32x32x16_bf16 v[32:47], v[88:91], v[156:159], v[32:47]
	s_waitcnt lgkmcnt(3)
	v_mfma_f32_32x32x16_bf16 v[48:63], v[64:67], v[168:171], v[48:63]
	s_waitcnt lgkmcnt(2)
	v_mfma_f32_32x32x16_bf16 v[48:63], v[68:71], v[164:167], v[48:63]
	s_waitcnt lgkmcnt(1)
	v_mfma_f32_32x32x16_bf16 v[48:63], v[76:79], v[160:163], v[48:63]
	s_waitcnt lgkmcnt(0)
	v_mfma_f32_32x32x16_bf16 v[48:63], v[80:83], v[156:159], v[48:63]
	v_ashrrev_i32_e32 v64, 2, v214
	v_mul_lo_u32 v65, v64, s93
	v_lshlrev_b32_e32 v66, 5, v74
	v_add3_u32 v65, 0, v65, v66
	ds_read_b128 v[66:69], v65 offset:34816
	ds_read_b128 v[70:73], v65 offset:34832
	s_waitcnt lgkmcnt(1)
	v_lshlrev_b32_e32 v65, 16, v66
	v_and_b32_e32 v66, 0xffff0000, v66
	v_add_f32_e32 v65, v65, v66
	s_waitcnt lgkmcnt(0)
	v_lshlrev_b32_e32 v66, 16, v70
	v_and_b32_e32 v70, 0xffff0000, v70
	v_add_f32_e32 v66, v66, v70
	v_add_f32_e32 v65, v65, v66
	v_lshlrev_b32_e32 v66, 16, v67
	v_and_b32_e32 v67, 0xffff0000, v67
	v_add_f32_e32 v66, v66, v67
	v_lshlrev_b32_e32 v67, 16, v71
	v_and_b32_e32 v70, 0xffff0000, v71
	v_add_f32_e32 v67, v67, v70
	v_add_f32_e32 v65, 0, v65
	v_add_f32_e32 v66, v66, v67
	v_add_f32_e32 v65, v66, v65
	v_lshlrev_b32_e32 v66, 16, v68
	v_and_b32_e32 v67, 0xffff0000, v68
	v_add_f32_e32 v66, v66, v67
	v_lshlrev_b32_e32 v67, 16, v72
	v_and_b32_e32 v68, 0xffff0000, v72
	v_add_f32_e32 v67, v67, v68
	v_add_f32_e32 v66, v66, v67
	v_add_f32_e32 v65, v66, v65
	v_lshlrev_b32_e32 v66, 16, v69
	v_and_b32_e32 v67, 0xffff0000, v69
	v_add_f32_e32 v66, v66, v67
	v_lshlrev_b32_e32 v67, 16, v73
	v_and_b32_e32 v68, 0xffff0000, v73
	v_add_f32_e32 v67, v67, v68
	v_add_f32_e32 v66, v66, v67
	v_add_f32_e32 v65, v66, v65
	ds_bpermute_b32 v66, v189, v65
	s_waitcnt lgkmcnt(0)
	v_add_f32_e32 v65, v65, v66
	ds_bpermute_b32 v66, v191, v65
	s_and_saveexec_b64 s[12:13], vcc
	s_cbranch_execz .LBB0_206
	v_lshl_add_u32 v64, v64, 2, 0
	v_add_u32_e32 v64, 0x21000, v64
	s_waitcnt lgkmcnt(0)
	v_add_f32_e32 v65, v65, v66
	ds_read_b32 v66, v64
	s_waitcnt lgkmcnt(0)
	v_fmac_f32_e32 v65, v96, v66
	ds_write_b32 v64, v65
	s_branch .LBB0_206
